# RESID epilogue: 8 row groups software-pipelined (2x4 loads in flight, addresses = group0+const)
# speedup vs baseline: 1.1365x; 1.0070x over previous
;   __device__ __forceinline__ void operator()(const f32x4 (&acc)[2][2][4][2], const pg8::Unit& u, int wr, int wc, int fr, int fq) const {
;     ...
;           float* xb;
;           { int b_ = row >= TPB ? 1 : 0; int u_ = row - b_ * TPB;
;             xb = (u_ < CTX) ? xctx + (size_t)(b_ * CTX + u_) * D : xout + ((size_t)b_ * SEQ + (u_ - CTX)) * D; }
;           const float* xr = (xb >= xout && xb < xout + (size_t)2 * SEQ * D) ? xin + (xb - xout) : xb;
; #pragma unroll
;           for (int bj = 0; bj < 2; ++bj)
; #pragma unroll
;             for (int n = 0; n < 2; ++n) {
;               int cc = u.pn * 256 + bj * 128 + wc * 32 + n * 16 + fq * 4;
;               const float4 gs = gsv[bj][n];
;               float4 xv = *(const float4*)(xr + cc);
;               f32x4 a = acc[ai][bj][m][n];
;               xv.x += gs.x * a[0]; xv.y += gs.y * a[1]; xv.z += gs.z * a[2]; xv.w += gs.w * a[3];
;               *(float4*)(xb + cc) = xv;
.LBB0_339:
	s_or_b64 exec, exec, s[4:5]
	v_lshlrev_b64 v[16:17], 12, v[16:17]
	v_lshl_add_u64 v[16:17], v[18:19], 0, v[16:17]
	v_cmp_le_u64_e32 vcc, s[44:45], v[16:17]
	v_cmp_gt_u64_e64 s[42:43], s[56:57], v[16:17]
	s_and_b64 vcc, vcc, s[42:43]
	v_subrev_co_u32_e64 v18, s[42:43], s44, v16
	v_mov_b32_e32 v19, s45
	s_nop 0
	v_subb_co_u32_e64 v19, s[42:43], v17, v19, s[42:43]
	v_lshl_add_u64 v[18:19], s[44:45], 0, v[18:19]
	v_cndmask_b32_e32 v19, v17, v19, vcc
	v_cndmask_b32_e32 v18, v16, v18, vcc
	v_lshl_add_u64 v[20:21], v[18:19], 0, v[152:153]
	v_lshl_add_u64 v[22:23], v[16:17], 0, v[152:153]
	s_and_b64 vcc, exec, s[40:41]
	s_mov_b32 s4, s58
	s_mov_b32 s42, s60
	s_mov_b64 s[8:9], s[64:65]
	s_mov_b64 s[6:7], s[62:63]
	s_cbranch_vccnz .LBB0_380

; #define PG8_STAGE(bufoff, gbase, voff) do { _Pragma("unroll") for (int _i = 0; _i < 2; ++_i) \
;         __builtin_amdgcn_global_load_lds((const unsigned*)((const char*)(gbase) + (voff)[_i]), (PG8_LAS unsigned*)(lds + (bufoff) + ldsw + _i * 8192), 16, 0, 0); } while (0)
; #define PG8_LDA(dst, b, h) do { _Pragma("unroll") for (int m = 0; m < 4; ++m) _Pragma("unroll") for (int k = 0; k < 2; ++k) dst[m][k] = *(const PG8_LAS bf16x8*)(lds + PG8_SA(b, h) + aoff + m * 2048 + k * 1024); } while (0)
; #define PG8_LDB(dst, b, h) do { _Pragma("unroll") for (int n = 0; n < 2; ++n) _Pragma("unroll") for (int k = 0; k < 2; ++k) dst[n][k] = *(const PG8_LAS bf16x8*)(lds + PG8_SB(b, h) + boff + n * 2048 + k * 1024); } while (0)
; #define PG8_MMA(ai, bj, At, Bt) do { __builtin_amdgcn_s_setprio(1); _Pragma("unroll") for (int m = 0; m < 4; ++m) _Pragma("unroll") for (int n = 0; n < 2; ++n) _Pragma("unroll") for (int k = 0; k < 2; ++k) \
;         acc[ai][bj][m][n] = __builtin_amdgcn_mfma_f32_16x16x32_bf16(Bt[n][k], At[m][k], acc[ai][bj][m][n], 0, 0, 0); __builtin_amdgcn_s_setprio(0); } while (0)
; template <class Epi>
; __device__ __forceinline__ void gemm_phase(PG8_LAS unsigned char* lds, const Gemm g, const Sched& S, const Epi& E) {
;     ...
;         const char* nA = has_next ? (const char*)g.A + (size_t)nxt.pm * tsA : cA; const char* nB = has_next ? (const char*)g.Bt + (size_t)nxt.pn * tsB : cB;
;         for (int t = 0; t < nt; t += 2) {
;             const bool last = (t == nt - 2);
;             const char* a1 = cA + (size_t)(t + 1) * kstep;
;             const char* a2 = last ? nA : cA + (size_t)(t + 2) * kstep; const char* b2 = last ? nB : cB + (size_t)(t + 2) * kstep;
;             const char* a3 = a2 + kstep; const char* b3 = b2 + kstep;
;             PG8_LDB(B0, 0, 0); PG8_SCHED; PG8_LDA(At, 0, 0); PG8_STAGE(PG8_SA(1, 1), a1 + hsA, voffA);
;             PG8_WAIT_L(8); PG8_BAR; PG8_WAIT_L(0); PG8_MMA(0, 0, At, B0); PG8_BAR; PG8_SCHED;
;             PG8_LDB(B1, 0, 1); PG8_STAGE(PG8_SB(0, 0), b2, voffB);
;             PG8_BAR; PG8_WAIT_L(0); PG8_MMA(0, 1, At, B1); PG8_BAR;
;             PG8_LDA(At, 0, 1); PG8_STAGE(PG8_SA(0, 0), a2, voffA);
;             PG8_BAR; PG8_WAIT_L(0); PG8_MMA(1, 0, At, B0); PG8_BAR; PG8_SCHED;
;             PG8_STAGE(PG8_SB(0, 1), b2 + hsB, voffB);
;             PG8_WAIT_V(6); PG8_BAR; PG8_MMA(1, 1, At, B1); PG8_BAR;
.LBB0_347:
	s_add_u32 s8, s6, 0xfffc0080
	s_addc_u32 s9, s7, -1
	s_add_i32 s39, 0, 0x10000
	v_add_u32_e32 v96, s39, v157
	ds_read_b128 v[80:83], v96
	ds_read_b128 v[84:87], v96 offset:1024
	ds_read_b128 v[88:91], v96 offset:2048
	ds_read_b128 v[96:99], v96 offset:3072
	s_cmp_eq_u32 s38, 12
	s_cselect_b32 s11, s2, s9
	s_cselect_b32 s10, s3, s8
	s_cselect_b32 s9, s5, s37
	s_cselect_b32 s8, s30, s36
	v_lshl_add_u64 v[202:203], s[6:7], 0, v[148:149]
	s_add_i32 m0, s15, 0xc000
	ds_read_b128 v[152:155], v162
	ds_read_b128 v[172:175], v162 offset:1024
	ds_read_b128 v[178:181], v162 offset:2048
	ds_read_b128 v[182:185], v162 offset:3072
	ds_read_b128 v[186:189], v162 offset:4096
	ds_read_b128 v[190:193], v162 offset:5120
	ds_read_b128 v[194:197], v162 offset:6144
	ds_read_b128 v[198:201], v162 offset:7168
	global_load_lds_dwordx4 v[202:203], off
	v_lshl_add_u64 v[202:203], s[6:7], 0, v[150:151]
	s_add_i32 m0, s15, 0xe000
	s_nop 0
	global_load_lds_dwordx4 v[202:203], off
	s_waitcnt lgkmcnt(8)
	s_barrier
	s_waitcnt lgkmcnt(0)
	s_setprio 1
	s_waitcnt lgkmcnt(0)
	v_mfma_f32_16x16x32_bf16 v[140:143], v[80:83], v[152:155], v[140:143]
	v_mfma_f32_16x16x32_bf16 v[136:139], v[88:91], v[152:155], v[136:139]
	v_mfma_f32_16x16x32_bf16 v[124:127], v[80:83], v[178:181], v[124:127]
	v_mfma_f32_16x16x32_bf16 v[120:123], v[88:91], v[178:181], v[120:123]
	v_mfma_f32_16x16x32_bf16 v[108:111], v[80:83], v[186:189], v[108:111]
	v_mfma_f32_16x16x32_bf16 v[104:107], v[88:91], v[186:189], v[104:107]
	v_mfma_f32_16x16x32_bf16 v[76:79], v[80:83], v[194:197], v[76:79]
	v_mfma_f32_16x16x32_bf16 v[72:75], v[88:91], v[194:197], v[72:75]
	v_mfma_f32_16x16x32_bf16 v[140:143], v[84:87], v[172:175], v[140:143]
	v_mfma_f32_16x16x32_bf16 v[136:139], v[96:99], v[172:175], v[136:139]
	v_mfma_f32_16x16x32_bf16 v[124:127], v[84:87], v[182:185], v[124:127]
	v_mfma_f32_16x16x32_bf16 v[120:123], v[96:99], v[182:185], v[120:123]
	v_mfma_f32_16x16x32_bf16 v[108:111], v[84:87], v[190:193], v[108:111]
	v_mfma_f32_16x16x32_bf16 v[104:107], v[96:99], v[190:193], v[104:107]
	v_mfma_f32_16x16x32_bf16 v[76:79], v[84:87], v[198:201], v[76:79]
	v_mfma_f32_16x16x32_bf16 v[72:75], v[96:99], v[198:201], v[72:75]
	s_setprio 0
	s_barrier
	s_add_i32 s43, 0, 0x14000
	s_add_i32 s39, s39, s14
	v_add_u32_e32 v166, s43, v157
	v_lshl_add_u64 v[214:215], s[8:9], 0, v[144:145]
	s_mov_b32 m0, s39
	ds_read_b128 v[202:205], v166
	ds_read_b128 v[206:209], v166 offset:1024
	ds_read_b128 v[210:213], v166 offset:2048
	ds_read_b128 v[236:239], v166 offset:3072
	global_load_lds_dwordx4 v[214:215], off
	v_lshl_add_u64 v[240:241], s[8:9], 0, v[146:147]
	s_add_i32 m0, s39, 0x2000
	s_nop 0
	global_load_lds_dwordx4 v[240:241], off
	s_barrier
	s_waitcnt lgkmcnt(0)
	s_setprio 1
	s_waitcnt lgkmcnt(0)
	v_mfma_f32_16x16x32_bf16 v[132:135], v[202:205], v[152:155], v[132:135]
	v_mfma_f32_16x16x32_bf16 v[128:131], v[210:213], v[152:155], v[128:131]
	v_mfma_f32_16x16x32_bf16 v[116:119], v[202:205], v[178:181], v[116:119]
	v_mfma_f32_16x16x32_bf16 v[112:115], v[210:213], v[178:181], v[112:115]
	v_mfma_f32_16x16x32_bf16 v[100:103], v[202:205], v[186:189], v[100:103]
	v_mfma_f32_16x16x32_bf16 v[92:95], v[210:213], v[186:189], v[92:95]
	v_mfma_f32_16x16x32_bf16 v[68:71], v[202:205], v[194:197], v[68:71]
	v_mfma_f32_16x16x32_bf16 v[64:67], v[210:213], v[194:197], v[64:67]
	v_mfma_f32_16x16x32_bf16 v[132:135], v[206:209], v[172:175], v[132:135]
	v_mfma_f32_16x16x32_bf16 v[128:131], v[236:239], v[172:175], v[128:131]
	v_mfma_f32_16x16x32_bf16 v[116:119], v[206:209], v[182:185], v[116:119]
	v_mfma_f32_16x16x32_bf16 v[112:115], v[236:239], v[182:185], v[112:115]
	v_mfma_f32_16x16x32_bf16 v[100:103], v[206:209], v[190:193], v[100:103]
	v_mfma_f32_16x16x32_bf16 v[92:95], v[236:239], v[190:193], v[92:95]
	v_mfma_f32_16x16x32_bf16 v[68:71], v[206:209], v[198:201], v[68:71]
	v_mfma_f32_16x16x32_bf16 v[64:67], v[236:239], v[198:201], v[64:67]
	s_setprio 0
	s_mov_b32 m0, s15
	v_lshl_add_u64 v[242:243], s[10:11], 0, v[144:145]
	s_barrier
	ds_read_b128 v[152:155], v162 offset:16384
	ds_read_b128 v[172:175], v162 offset:17408
	ds_read_b128 v[178:181], v162 offset:18432
	ds_read_b128 v[182:185], v162 offset:19456
	ds_read_b128 v[186:189], v162 offset:20480
	ds_read_b128 v[190:193], v162 offset:21504
	ds_read_b128 v[194:197], v162 offset:22528
	ds_read_b128 v[198:201], v162 offset:23552
	global_load_lds_dwordx4 v[242:243], off
	v_lshl_add_u64 v[244:245], s[10:11], 0, v[146:147]
	s_mov_b32 m0, s16
	s_nop 0
	global_load_lds_dwordx4 v[244:245], off
	s_barrier
	s_waitcnt lgkmcnt(0)
	s_setprio 1
	s_waitcnt lgkmcnt(0)
	v_mfma_f32_16x16x32_bf16 v[60:63], v[80:83], v[152:155], v[60:63]
	v_mfma_f32_16x16x32_bf16 v[56:59], v[88:91], v[152:155], v[56:59]
	v_mfma_f32_16x16x32_bf16 v[44:47], v[80:83], v[178:181], v[44:47]
	v_mfma_f32_16x16x32_bf16 v[40:43], v[88:91], v[178:181], v[40:43]
	v_mfma_f32_16x16x32_bf16 v[28:31], v[80:83], v[186:189], v[28:31]
	v_mfma_f32_16x16x32_bf16 v[24:27], v[88:91], v[186:189], v[24:27]
	v_mfma_f32_16x16x32_bf16 v[12:15], v[80:83], v[194:197], v[12:15]
	v_mfma_f32_16x16x32_bf16 v[8:11], v[88:91], v[194:197], v[8:11]
	v_mfma_f32_16x16x32_bf16 v[60:63], v[84:87], v[172:175], v[60:63]
	v_mfma_f32_16x16x32_bf16 v[56:59], v[96:99], v[172:175], v[56:59]
	v_mfma_f32_16x16x32_bf16 v[44:47], v[84:87], v[182:185], v[44:47]
	v_mfma_f32_16x16x32_bf16 v[40:43], v[96:99], v[182:185], v[40:43]
	v_mfma_f32_16x16x32_bf16 v[28:31], v[84:87], v[190:193], v[28:31]
	v_mfma_f32_16x16x32_bf16 v[24:27], v[96:99], v[190:193], v[24:27]
	v_mfma_f32_16x16x32_bf16 v[12:15], v[84:87], v[198:201], v[12:15]
	v_mfma_f32_16x16x32_bf16 v[8:11], v[96:99], v[198:201], v[8:11]
	s_setprio 0
	s_barrier
; #define PG8_STAGE(bufoff, gbase, voff) do { _Pragma("unroll") for (int _i = 0; _i < 2; ++_i) \
;         __builtin_amdgcn_global_load_lds((const unsigned*)((const char*)(gbase) + (voff)[_i]), (PG8_LAS unsigned*)(lds + (bufoff) + ldsw + _i * 8192), 16, 0, 0); } while (0)
; #define PG8_LDA(dst, b, h) do { _Pragma("unroll") for (int m = 0; m < 4; ++m) _Pragma("unroll") for (int k = 0; k < 2; ++k) dst[m][k] = *(const PG8_LAS bf16x8*)(lds + PG8_SA(b, h) + aoff + m * 2048 + k * 1024); } while (0)
; #define PG8_LDB(dst, b, h) do { _Pragma("unroll") for (int n = 0; n < 2; ++n) _Pragma("unroll") for (int k = 0; k < 2; ++k) dst[n][k] = *(const PG8_LAS bf16x8*)(lds + PG8_SB(b, h) + boff + n * 2048 + k * 1024); } while (0)
; #define PG8_MMA(ai, bj, At, Bt) do { __builtin_amdgcn_s_setprio(1); _Pragma("unroll") for (int m = 0; m < 4; ++m) _Pragma("unroll") for (int n = 0; n < 2; ++n) _Pragma("unroll") for (int k = 0; k < 2; ++k) \
;         acc[ai][bj][m][n] = __builtin_amdgcn_mfma_f32_16x16x32_bf16(Bt[n][k], At[m][k], acc[ai][bj][m][n], 0, 0, 0); __builtin_amdgcn_s_setprio(0); } while (0)
; #define PG8_WAIT_V(n) asm volatile("s_waitcnt vmcnt(" #n ")" ::: "memory")
; #define PG8_WAIT_L(n) asm volatile("s_waitcnt lgkmcnt(" #n ")" ::: "memory")
; #define PG8_BAR __builtin_amdgcn_s_barrier()
; #define PG8_SCHED __builtin_amdgcn_sched_barrier(0)
; template <class Epi>
; __device__ __forceinline__ void gemm_phase(PG8_LAS unsigned char* lds, const Gemm g, const Sched& S, const Epi& E) {
;     ...
;             PG8_BAR; PG8_WAIT_L(0); PG8_MMA(1, 0, At, B0); PG8_BAR; PG8_SCHED;
;             PG8_STAGE(PG8_SB(0, 1), b2 + hsB, voffB);
;             PG8_WAIT_V(6); PG8_BAR; PG8_MMA(1, 1, At, B1); PG8_BAR;
;             PG8_LDB(B0, 1, 0); PG8_SCHED; PG8_LDA(At, 1, 0); PG8_STAGE(PG8_SA(0, 1), a2 + hsA, voffA);
;             PG8_WAIT_L(8); PG8_BAR; PG8_WAIT_L(0); PG8_MMA(0, 0, At, B0); PG8_BAR; PG8_SCHED;
;             PG8_LDB(B1, 1, 1); PG8_STAGE(PG8_SB(1, 0), b3, voffB);
;             PG8_BAR; PG8_WAIT_L(0); PG8_MMA(0, 1, At, B1); PG8_BAR;
;             PG8_LDA(At, 1, 1); PG8_STAGE(PG8_SA(1, 0), a3, voffA);
;             PG8_BAR; PG8_WAIT_L(0); PG8_MMA(1, 0, At, B0); PG8_BAR; PG8_SCHED;
	s_add_u32 s66, s8, 0x40000
	s_addc_u32 s67, s9, 0
	s_add_i32 s39, s43, s14
	v_lshl_add_u64 v[80:81], s[66:67], 0, v[144:145]
	s_mov_b32 m0, s39
	s_nop 0
	global_load_lds_dwordx4 v[80:81], off
	v_lshl_add_u64 v[80:81], s[66:67], 0, v[146:147]
	s_add_i32 m0, s39, 0x2000
	s_nop 0
	global_load_lds_dwordx4 v[80:81], off
	s_waitcnt vmcnt(6)
	s_barrier
	s_setprio 1
	v_mfma_f32_16x16x32_bf16 v[52:55], v[202:205], v[152:155], v[52:55]
	v_mfma_f32_16x16x32_bf16 v[48:51], v[210:213], v[152:155], v[48:51]
	v_mfma_f32_16x16x32_bf16 v[36:39], v[202:205], v[178:181], v[36:39]
	v_mfma_f32_16x16x32_bf16 v[32:35], v[210:213], v[178:181], v[32:35]
	v_mfma_f32_16x16x32_bf16 v[20:23], v[202:205], v[186:189], v[20:23]
	v_mfma_f32_16x16x32_bf16 v[16:19], v[210:213], v[186:189], v[16:19]
	v_mfma_f32_16x16x32_bf16 v[4:7], v[202:205], v[194:197], v[4:7]
	v_mfma_f32_16x16x32_bf16 v[0:3], v[210:213], v[194:197], v[0:3]
	v_mfma_f32_16x16x32_bf16 v[52:55], v[206:209], v[172:175], v[52:55]
	v_mfma_f32_16x16x32_bf16 v[48:51], v[236:239], v[172:175], v[48:51]
	v_mfma_f32_16x16x32_bf16 v[36:39], v[206:209], v[182:185], v[36:39]
	v_mfma_f32_16x16x32_bf16 v[32:35], v[236:239], v[182:185], v[32:35]
	v_mfma_f32_16x16x32_bf16 v[20:23], v[206:209], v[190:193], v[20:23]
	v_mfma_f32_16x16x32_bf16 v[16:19], v[236:239], v[190:193], v[16:19]
	v_mfma_f32_16x16x32_bf16 v[4:7], v[206:209], v[198:201], v[4:7]
	v_mfma_f32_16x16x32_bf16 v[0:3], v[236:239], v[198:201], v[0:3]
	s_setprio 0
	s_add_i32 s39, 0, 0x18000
	v_add_u32_e32 v96, s39, v157
	s_barrier
	ds_read_b128 v[80:83], v96
	ds_read_b128 v[84:87], v96 offset:1024
	ds_read_b128 v[88:91], v96 offset:2048
	ds_read_b128 v[96:99], v96 offset:3072
	s_add_u32 s10, s10, 0x40000
	s_addc_u32 s11, s11, 0
	s_mov_b32 m0, s17
	v_lshl_add_u64 v[202:203], s[10:11], 0, v[144:145]
	ds_read_b128 v[152:155], v162 offset:32768
	ds_read_b128 v[172:175], v162 offset:33792
	ds_read_b128 v[178:181], v162 offset:34816
	ds_read_b128 v[182:185], v162 offset:35840
	ds_read_b128 v[186:189], v162 offset:36864
	ds_read_b128 v[190:193], v162 offset:37888
	ds_read_b128 v[194:197], v162 offset:38912
	ds_read_b128 v[198:201], v162 offset:39936
	global_load_lds_dwordx4 v[202:203], off
	v_lshl_add_u64 v[202:203], s[10:11], 0, v[146:147]
	s_mov_b32 m0, s20
	s_nop 0
	global_load_lds_dwordx4 v[202:203], off
	s_waitcnt lgkmcnt(8)
	s_barrier
	s_waitcnt lgkmcnt(0)
	s_setprio 1
	s_waitcnt lgkmcnt(0)
	v_mfma_f32_16x16x32_bf16 v[140:143], v[80:83], v[152:155], v[140:143]
	v_mfma_f32_16x16x32_bf16 v[136:139], v[88:91], v[152:155], v[136:139]
	v_mfma_f32_16x16x32_bf16 v[124:127], v[80:83], v[178:181], v[124:127]
	v_mfma_f32_16x16x32_bf16 v[120:123], v[88:91], v[178:181], v[120:123]
	v_mfma_f32_16x16x32_bf16 v[108:111], v[80:83], v[186:189], v[108:111]
	v_mfma_f32_16x16x32_bf16 v[104:107], v[88:91], v[186:189], v[104:107]
	v_mfma_f32_16x16x32_bf16 v[76:79], v[80:83], v[194:197], v[76:79]
	v_mfma_f32_16x16x32_bf16 v[72:75], v[88:91], v[194:197], v[72:75]
	v_mfma_f32_16x16x32_bf16 v[140:143], v[84:87], v[172:175], v[140:143]
	v_mfma_f32_16x16x32_bf16 v[136:139], v[96:99], v[172:175], v[136:139]
	v_mfma_f32_16x16x32_bf16 v[124:127], v[84:87], v[182:185], v[124:127]
	v_mfma_f32_16x16x32_bf16 v[120:123], v[96:99], v[182:185], v[120:123]
	v_mfma_f32_16x16x32_bf16 v[108:111], v[84:87], v[190:193], v[108:111]
	v_mfma_f32_16x16x32_bf16 v[104:107], v[96:99], v[190:193], v[104:107]
	v_mfma_f32_16x16x32_bf16 v[76:79], v[84:87], v[198:201], v[76:79]
	v_mfma_f32_16x16x32_bf16 v[72:75], v[96:99], v[198:201], v[72:75]
	s_setprio 0
	s_barrier
	s_add_i32 s10, 0, 0x1c000
	s_add_i32 s11, s39, s14
	v_add_u32_e32 v166, s10, v157
	v_lshl_add_u64 v[214:215], v[214:215], 0, s[76:77]
	s_mov_b32 m0, s11
	ds_read_b128 v[202:205], v166
	ds_read_b128 v[206:209], v166 offset:1024
	ds_read_b128 v[210:213], v166 offset:2048
	ds_read_b128 v[236:239], v166 offset:3072
	global_load_lds_dwordx4 v[214:215], off
	v_lshl_add_u64 v[214:215], v[240:241], 0, s[76:77]
	s_add_i32 m0, s11, 0x2000
	s_nop 0
	global_load_lds_dwordx4 v[214:215], off
	s_barrier
	s_waitcnt lgkmcnt(0)
	s_setprio 1
	s_waitcnt lgkmcnt(0)
	v_mfma_f32_16x16x32_bf16 v[132:135], v[202:205], v[152:155], v[132:135]
	v_mfma_f32_16x16x32_bf16 v[128:131], v[210:213], v[152:155], v[128:131]
	v_mfma_f32_16x16x32_bf16 v[116:119], v[202:205], v[178:181], v[116:119]
	v_mfma_f32_16x16x32_bf16 v[112:115], v[210:213], v[178:181], v[112:115]
	v_mfma_f32_16x16x32_bf16 v[100:103], v[202:205], v[186:189], v[100:103]
	v_mfma_f32_16x16x32_bf16 v[92:95], v[210:213], v[186:189], v[92:95]
	v_mfma_f32_16x16x32_bf16 v[68:71], v[202:205], v[194:197], v[68:71]
	v_mfma_f32_16x16x32_bf16 v[64:67], v[210:213], v[194:197], v[64:67]
	v_mfma_f32_16x16x32_bf16 v[132:135], v[206:209], v[172:175], v[132:135]
	v_mfma_f32_16x16x32_bf16 v[128:131], v[236:239], v[172:175], v[128:131]
	v_mfma_f32_16x16x32_bf16 v[116:119], v[206:209], v[182:185], v[116:119]
	v_mfma_f32_16x16x32_bf16 v[112:115], v[236:239], v[182:185], v[112:115]
	v_mfma_f32_16x16x32_bf16 v[100:103], v[206:209], v[190:193], v[100:103]
	v_mfma_f32_16x16x32_bf16 v[92:95], v[236:239], v[190:193], v[92:95]
	v_mfma_f32_16x16x32_bf16 v[68:71], v[206:209], v[198:201], v[68:71]
	v_mfma_f32_16x16x32_bf16 v[64:67], v[236:239], v[198:201], v[64:67]
	s_setprio 0
	s_mov_b32 m0, s21
	v_lshl_add_u64 v[214:215], v[242:243], 0, s[76:77]
	s_barrier
	ds_read_b128 v[152:155], v162 offset:49152
	ds_read_b128 v[172:175], v162 offset:50176
	ds_read_b128 v[178:181], v162 offset:51200
	ds_read_b128 v[182:185], v162 offset:52224
	ds_read_b128 v[186:189], v162 offset:53248
	ds_read_b128 v[190:193], v162 offset:54272
	ds_read_b128 v[194:197], v162 offset:55296
	ds_read_b128 v[198:201], v162 offset:56320
	global_load_lds_dwordx4 v[214:215], off
	v_lshl_add_u64 v[214:215], v[244:245], 0, s[76:77]
	s_mov_b32 m0, s22
	s_nop 0
	global_load_lds_dwordx4 v[214:215], off
	s_barrier
; #define PG8_WAIT_V(n) asm volatile("s_waitcnt vmcnt(" #n ")" ::: "memory")
; template <class Epi>
; __device__ __forceinline__ void gemm_phase(PG8_LAS unsigned char* lds, const Gemm g, const Sched& S, const Epi& E) {
;     ...
;             PG8_BAR; PG8_WAIT_L(0); PG8_MMA(1, 0, At, B0); PG8_BAR; PG8_SCHED;
;             PG8_STAGE(PG8_SB(1, 1), b3 + hsB, voffB);
;             PG8_WAIT_V(6); PG8_BAR; PG8_MMA(1, 1, At, B1); PG8_BAR;
;         }
;         E(acc, cur, wr, wc, fr, fq);
;   __device__ __forceinline__ void operator()(const f32x4 (&acc)[2][2][4][2], const pg8::Unit& u, int wr, int wc, int fr, int fq) const {
;     ...
;     if (kind == EPI_RESID) {
;       const float* md0 = modp + ((size_t)layer * 3 + condof(u.pm * 256)) * NMOD + slot * D;
; #pragma unroll
;       for (int bj = 0; bj < 2; ++bj)
; #pragma unroll
;         for (int n = 0; n < 2; ++n) {
;           float4 t = *(const float4*)(md0 + u.pn * 256 + bj * 128 + wc * 32 + n * 16 + fq * 4);
;           gsv[bj][n] = make_float4(t.x * scale, t.y * scale, t.z * scale, t.w * scale);
;         }
;     }
; #pragma unroll
;     for (int ai = 0; ai < 2; ++ai)
; #pragma unroll
;       for (int m = 0; m < 4; ++m) {
;         const int row = u.pm * 256 + ai * 128 + wr * 64 + m * 16 + fr;
;         if (kind == EPI_SWIGLU) {
; #pragma unroll
;           for (int bj = 0; bj < 2; ++bj) {
;             int hc = u.pn * 128 + bj * 64 + wc * 16 + fq * 4;
;             f32x4 g = acc[ai][bj][m][0], up = acc[ai][bj][m][1];
;             uint2 o; o.x = pack2(siluf_(g[0]) * up[0], siluf_(g[1]) * up[1]); o.y = pack2(siluf_(g[2]) * up[2], siluf_(g[3]) * up[3]);
;             *(uint2*)(outb + (size_t)row * ldo + hc) = o;
;           }
;         } else if (kind == EPI_RESID) {
;           float* xb;
;           { int b_ = row >= TPB ? 1 : 0; int u_ = row - b_ * TPB;
;             xb = (u_ < CTX) ? xctx + (size_t)(b_ * CTX + u_) * D : xout + ((size_t)b_ * SEQ + (u_ - CTX)) * D; }
;           const float* xr = (xb >= xout && xb < xout + (size_t)2 * SEQ * D) ? xin + (xb - xout) : xb;
; #pragma unroll
;           for (int bj = 0; bj < 2; ++bj)
; #pragma unroll
;             for (int n = 0; n < 2; ++n) {
;               int cc = u.pn * 256 + bj * 128 + wc * 32 + n * 16 + fq * 4;
;               const float4 gs = gsv[bj][n];
;               float4 xv = *(const float4*)(xr + cc);
;               f32x4 a = acc[ai][bj][m][n];
	s_waitcnt lgkmcnt(0)
	s_setprio 1
	s_waitcnt lgkmcnt(0)
	v_mfma_f32_16x16x32_bf16 v[60:63], v[80:83], v[152:155], v[60:63]
	v_mfma_f32_16x16x32_bf16 v[56:59], v[88:91], v[152:155], v[56:59]
	v_mfma_f32_16x16x32_bf16 v[44:47], v[80:83], v[178:181], v[44:47]
	v_mfma_f32_16x16x32_bf16 v[40:43], v[88:91], v[178:181], v[40:43]
	v_mfma_f32_16x16x32_bf16 v[28:31], v[80:83], v[186:189], v[28:31]
	v_mfma_f32_16x16x32_bf16 v[24:27], v[88:91], v[186:189], v[24:27]
	v_mfma_f32_16x16x32_bf16 v[12:15], v[80:83], v[194:197], v[12:15]
	v_mfma_f32_16x16x32_bf16 v[8:11], v[88:91], v[194:197], v[8:11]
	v_mfma_f32_16x16x32_bf16 v[60:63], v[84:87], v[172:175], v[60:63]
	v_mfma_f32_16x16x32_bf16 v[56:59], v[96:99], v[172:175], v[56:59]
	v_mfma_f32_16x16x32_bf16 v[44:47], v[84:87], v[182:185], v[44:47]
	v_mfma_f32_16x16x32_bf16 v[40:43], v[96:99], v[182:185], v[40:43]
	v_mfma_f32_16x16x32_bf16 v[28:31], v[84:87], v[190:193], v[28:31]
	v_mfma_f32_16x16x32_bf16 v[24:27], v[96:99], v[190:193], v[24:27]
	v_mfma_f32_16x16x32_bf16 v[12:15], v[84:87], v[198:201], v[12:15]
	v_mfma_f32_16x16x32_bf16 v[8:11], v[96:99], v[198:201], v[8:11]
	s_setprio 0
	s_barrier
	s_add_u32 s8, s8, 0x40080
	s_addc_u32 s9, s9, 0
	s_add_i32 s10, s10, s14
	v_lshl_add_u64 v[80:81], s[8:9], 0, v[144:145]
	s_mov_b32 m0, s10
	s_nop 0
	global_load_lds_dwordx4 v[80:81], off
	v_lshl_add_u64 v[80:81], s[8:9], 0, v[146:147]
	s_add_i32 m0, s10, 0x2000
	s_nop 0
	global_load_lds_dwordx4 v[80:81], off
	s_waitcnt vmcnt(6)
	s_barrier
	s_setprio 1
	v_mfma_f32_16x16x32_bf16 v[52:55], v[202:205], v[152:155], v[52:55]
	v_mfma_f32_16x16x32_bf16 v[48:51], v[210:213], v[152:155], v[48:51]
	v_mfma_f32_16x16x32_bf16 v[36:39], v[202:205], v[178:181], v[36:39]
	v_mfma_f32_16x16x32_bf16 v[32:35], v[210:213], v[178:181], v[32:35]
	v_mfma_f32_16x16x32_bf16 v[20:23], v[202:205], v[186:189], v[20:23]
	v_mfma_f32_16x16x32_bf16 v[16:19], v[210:213], v[186:189], v[16:19]
	v_mfma_f32_16x16x32_bf16 v[4:7], v[202:205], v[194:197], v[4:7]
	v_mfma_f32_16x16x32_bf16 v[0:3], v[210:213], v[194:197], v[0:3]
	v_mfma_f32_16x16x32_bf16 v[52:55], v[206:209], v[172:175], v[52:55]
	v_mfma_f32_16x16x32_bf16 v[48:51], v[236:239], v[172:175], v[48:51]
	v_mfma_f32_16x16x32_bf16 v[36:39], v[206:209], v[182:185], v[36:39]
	v_mfma_f32_16x16x32_bf16 v[32:35], v[236:239], v[182:185], v[32:35]
	v_mfma_f32_16x16x32_bf16 v[20:23], v[206:209], v[190:193], v[20:23]
	v_mfma_f32_16x16x32_bf16 v[16:19], v[236:239], v[190:193], v[16:19]
	v_mfma_f32_16x16x32_bf16 v[4:7], v[206:209], v[198:201], v[4:7]
	v_mfma_f32_16x16x32_bf16 v[0:3], v[236:239], v[198:201], v[0:3]
	s_setprio 0
	s_add_i32 s38, s38, 2
	s_add_u32 s6, s6, 0x100
	s_addc_u32 s7, s7, 0
	s_add_u32 s36, s36, 0x100
	s_addc_u32 s37, s37, 0
	s_cmp_gt_u32 s38, 13
	s_barrier
	s_cbranch_scc0 .LBB0_347
	s_lshl_b32 s8, s42, 8
	s_cmp_gt_i32 s42, 32
	s_cselect_b64 s[2:3], -1, 0
	v_cndmask_b32_e64 v80, 0, 1, s[2:3]
	s_and_b64 s[2:3], s[2:3], exec
	s_cselect_b32 s2, 0xffffdf00, 0
	s_add_i32 s2, s2, s8
	s_cmpk_gt_i32 s2, 0xff
	v_readfirstlane_b32 s2, v80
	s_cselect_b32 s2, s2, 2
	s_add_i32 s2, s2, s24
	s_mul_i32 s2, s2, 0x9000
	s_add_u32 s6, s25, s2
	s_addc_u32 s7, s26, 0
	s_lshl_b32 s4, s4, 8
	s_ashr_i32 s5, s4, 31
	s_lshl_b64 s[2:3], s[4:5], 2
	s_add_u32 s2, s6, s2
	s_addc_u32 s3, s7, s3
	s_add_u32 s2, s2, s29
	s_addc_u32 s3, s3, 0
	global_load_dwordx4 v[96:99], v163, s[2:3]
	global_load_dwordx4 v[88:91], v163, s[2:3] offset:64
	global_load_dwordx4 v[84:87], v163, s[2:3] offset:512
	global_load_dwordx4 v[80:83], v163, s[2:3] offset:576
	v_add_u32_e32 v171, s8, v156
	s_movk_i32 s2, 0x20ff
	v_cmp_lt_i32_e32 vcc, s2, v171
	s_nop 1
	v_cndmask_b32_e32 v152, 0, v228, vcc
	v_add_u32_e32 v166, v152, v171
	v_cmp_lt_i32_e64 s[42:43], s81, v166
	s_and_saveexec_b64 s[2:3], s[42:43]
	s_xor_b64 s[2:3], exec, s[2:3]
	v_cndmask_b32_e32 v152, 0, v230, vcc
	s_movk_i32 s5, 0xff00
	v_add3_u32 v166, v166, v152, s5
	v_mov_b64_e32 v[152:153], v[166:167]
	s_or_saveexec_b64 s[6:7], s[2:3]
	v_mov_b64_e32 v[154:155], s[44:45]
	s_xor_b64 exec, exec, s[6:7]
	v_cndmask_b32_e32 v152, 0, v229, vcc
	v_add_u32_e32 v152, v166, v152
	v_ashrrev_i32_e32 v153, 31, v152
	v_mov_b64_e32 v[154:155], s[48:49]
	s_or_b64 exec, exec, s[6:7]
	v_lshlrev_b64 v[152:153], 12, v[152:153]
	v_lshl_add_u64 v[154:155], v[154:155], 0, v[152:153]
	v_cmp_le_u64_e32 vcc, s[44:45], v[154:155]
	v_cmp_gt_u64_e64 s[42:43], s[56:57], v[154:155]
	s_and_b64 vcc, vcc, s[42:43]
	v_subrev_co_u32_e64 v152, s[42:43], s44, v154
	v_mov_b32_e32 v153, s45
	s_nop 0
	v_subb_co_u32_e64 v153, s[42:43], v155, v153, s[42:43]
	v_lshl_add_u64 v[152:153], s[44:45], 0, v[152:153]
	v_cndmask_b32_e32 v172, v154, v152, vcc
	v_or_b32_e32 v152, s4, v158
	v_cndmask_b32_e32 v173, v155, v153, vcc
	v_ashrrev_i32_e32 v153, 31, v152
	v_lshlrev_b64 v[152:153], 2, v[152:153]
	v_lshl_add_u64 v[178:179], v[172:173], 0, v[152:153]
	global_load_dwordx4 v[180:183], v[178:179], off
	global_load_dwordx4 v[184:187], v[178:179], off offset:64
	global_load_dwordx4 v[188:191], v[178:179], off offset:512
	global_load_dwordx4 v[192:195], v[178:179], off offset:576
	v_lshl_add_u64 v[154:155], v[154:155], 0, v[152:153]
	s_movk_i32 s2, 0x20ff
	v_add_co_u32_e32 v212, vcc, 0x10000, v178
	s_nop 1
	v_addc_co_u32_e32 v213, vcc, 0, v179, vcc
	global_load_dwordx4 v[196:199], v[212:213], off
	global_load_dwordx4 v[200:203], v[212:213], off offset:64
	global_load_dwordx4 v[204:207], v[212:213], off offset:512
	global_load_dwordx4 v[208:211], v[212:213], off offset:576
	s_waitcnt vmcnt(7)
	v_pk_fma_f32 v[140:141], v[140:141], v[96:97], v[180:181]
	v_pk_fma_f32 v[142:143], v[142:143], v[98:99], v[182:183]
	global_store_dwordx4 v[154:155], v[140:143], off
	s_waitcnt vmcnt(7)
;   __device__ __forceinline__ void operator()(const f32x4 (&acc)[2][2][4][2], const pg8::Unit& u, int wr, int wc, int fr, int fq) const {
;     ...
;           float* xb;
;           { int b_ = row >= TPB ? 1 : 0; int u_ = row - b_ * TPB;
;             xb = (u_ < CTX) ? xctx + (size_t)(b_ * CTX + u_) * D : xout + ((size_t)b_ * SEQ + (u_ - CTX)) * D; }
;           const float* xr = (xb >= xout && xb < xout + (size_t)2 * SEQ * D) ? xin + (xb - xout) : xb;
; #pragma unroll
;           for (int bj = 0; bj < 2; ++bj)
; #pragma unroll
;             for (int n = 0; n < 2; ++n) {
;               int cc = u.pn * 256 + bj * 128 + wc * 32 + n * 16 + fq * 4;
;               const float4 gs = gsv[bj][n];
;               float4 xv = *(const float4*)(xr + cc);
;               f32x4 a = acc[ai][bj][m][n];
;               xv.x += gs.x * a[0]; xv.y += gs.y * a[1]; xv.z += gs.z * a[2]; xv.w += gs.w * a[3];
;               *(float4*)(xb + cc) = xv;
	v_pk_fma_f32 v[136:137], v[136:137], v[88:89], v[184:185]
	v_pk_fma_f32 v[138:139], v[138:139], v[90:91], v[186:187]
	global_store_dwordx4 v[154:155], v[136:139], off offset:64
	s_waitcnt vmcnt(7)
	v_pk_fma_f32 v[132:133], v[132:133], v[84:85], v[188:189]
	v_pk_fma_f32 v[134:135], v[134:135], v[86:87], v[190:191]
	global_store_dwordx4 v[154:155], v[132:135], off offset:512
	s_waitcnt vmcnt(7)
	v_pk_fma_f32 v[128:129], v[128:129], v[80:81], v[192:193]
	v_pk_fma_f32 v[130:131], v[130:131], v[82:83], v[194:195]
	global_store_dwordx4 v[154:155], v[128:131], off offset:576
	v_add_co_u32_e32 v212, vcc, 0x20000, v178
	s_nop 1
	v_addc_co_u32_e32 v213, vcc, 0, v179, vcc
	global_load_dwordx4 v[180:183], v[212:213], off
	global_load_dwordx4 v[184:187], v[212:213], off offset:64
	global_load_dwordx4 v[188:191], v[212:213], off offset:512
	global_load_dwordx4 v[192:195], v[212:213], off offset:576
	v_add_co_u32_e32 v236, vcc, 0x10000, v154
	s_nop 1
	v_addc_co_u32_e32 v237, vcc, 0, v155, vcc
	s_waitcnt vmcnt(11)
	v_pk_fma_f32 v[124:125], v[124:125], v[96:97], v[196:197]
	v_pk_fma_f32 v[126:127], v[126:127], v[98:99], v[198:199]
	global_store_dwordx4 v[236:237], v[124:127], off
	s_waitcnt vmcnt(11)
	v_pk_fma_f32 v[120:121], v[120:121], v[88:89], v[200:201]
	v_pk_fma_f32 v[122:123], v[122:123], v[90:91], v[202:203]
	global_store_dwordx4 v[236:237], v[120:123], off offset:64
	s_waitcnt vmcnt(11)
	v_pk_fma_f32 v[116:117], v[116:117], v[84:85], v[204:205]
	v_pk_fma_f32 v[118:119], v[118:119], v[86:87], v[206:207]
	global_store_dwordx4 v[236:237], v[116:119], off offset:512
	s_waitcnt vmcnt(11)
	v_pk_fma_f32 v[112:113], v[112:113], v[80:81], v[208:209]
	v_pk_fma_f32 v[114:115], v[114:115], v[82:83], v[210:211]
	global_store_dwordx4 v[236:237], v[112:115], off offset:576
	v_add_co_u32_e32 v212, vcc, 0x30000, v178
	s_nop 1
	v_addc_co_u32_e32 v213, vcc, 0, v179, vcc
	global_load_dwordx4 v[196:199], v[212:213], off
	global_load_dwordx4 v[200:203], v[212:213], off offset:64
	global_load_dwordx4 v[204:207], v[212:213], off offset:512
	global_load_dwordx4 v[208:211], v[212:213], off offset:576
	v_add_co_u32_e32 v236, vcc, 0x20000, v154
	s_nop 1
	v_addc_co_u32_e32 v237, vcc, 0, v155, vcc
	s_waitcnt vmcnt(11)
	v_pk_fma_f32 v[108:109], v[108:109], v[96:97], v[180:181]
	v_pk_fma_f32 v[110:111], v[110:111], v[98:99], v[182:183]
	global_store_dwordx4 v[236:237], v[108:111], off
	s_waitcnt vmcnt(11)
	v_pk_fma_f32 v[104:105], v[104:105], v[88:89], v[184:185]
	v_pk_fma_f32 v[106:107], v[106:107], v[90:91], v[186:187]
	global_store_dwordx4 v[236:237], v[104:107], off offset:64
	s_waitcnt vmcnt(11)
	v_pk_fma_f32 v[100:101], v[100:101], v[84:85], v[188:189]
	v_pk_fma_f32 v[102:103], v[102:103], v[86:87], v[190:191]
	global_store_dwordx4 v[236:237], v[100:103], off offset:512
	s_waitcnt vmcnt(11)
	v_pk_fma_f32 v[92:93], v[92:93], v[80:81], v[192:193]
	v_pk_fma_f32 v[94:95], v[94:95], v[82:83], v[194:195]
	global_store_dwordx4 v[236:237], v[92:95], off offset:576
	v_add_co_u32_e32 v212, vcc, 0x80000, v178
	s_nop 1
	v_addc_co_u32_e32 v213, vcc, 0, v179, vcc
	global_load_dwordx4 v[180:183], v[212:213], off
	global_load_dwordx4 v[184:187], v[212:213], off offset:64
	global_load_dwordx4 v[188:191], v[212:213], off offset:512
	global_load_dwordx4 v[192:195], v[212:213], off offset:576
	v_add_co_u32_e32 v236, vcc, 0x30000, v154
	s_nop 1
	v_addc_co_u32_e32 v237, vcc, 0, v155, vcc
	s_waitcnt vmcnt(11)
	v_pk_fma_f32 v[76:77], v[76:77], v[96:97], v[196:197]
	v_pk_fma_f32 v[78:79], v[78:79], v[98:99], v[198:199]
	global_store_dwordx4 v[236:237], v[76:79], off
	s_waitcnt vmcnt(11)
	v_pk_fma_f32 v[72:73], v[72:73], v[88:89], v[200:201]
	v_pk_fma_f32 v[74:75], v[74:75], v[90:91], v[202:203]
	global_store_dwordx4 v[236:237], v[72:75], off offset:64
	s_waitcnt vmcnt(11)
	v_pk_fma_f32 v[68:69], v[68:69], v[84:85], v[204:205]
	v_pk_fma_f32 v[70:71], v[70:71], v[86:87], v[206:207]
	global_store_dwordx4 v[236:237], v[68:71], off offset:512
	s_waitcnt vmcnt(11)
	v_pk_fma_f32 v[64:65], v[64:65], v[80:81], v[208:209]
	v_pk_fma_f32 v[66:67], v[66:67], v[82:83], v[210:211]
	global_store_dwordx4 v[236:237], v[64:67], off offset:576
	v_add_co_u32_e32 v212, vcc, 0x90000, v178
	s_nop 1
	v_addc_co_u32_e32 v213, vcc, 0, v179, vcc
	global_load_dwordx4 v[196:199], v[212:213], off
	global_load_dwordx4 v[200:203], v[212:213], off offset:64
	global_load_dwordx4 v[204:207], v[212:213], off offset:512
	global_load_dwordx4 v[208:211], v[212:213], off offset:576
	v_add_co_u32_e32 v236, vcc, 0x80000, v154
	s_nop 1
	v_addc_co_u32_e32 v237, vcc, 0, v155, vcc
	s_waitcnt vmcnt(11)
	v_pk_fma_f32 v[60:61], v[60:61], v[96:97], v[180:181]
	v_pk_fma_f32 v[62:63], v[62:63], v[98:99], v[182:183]
	global_store_dwordx4 v[236:237], v[60:63], off
	s_waitcnt vmcnt(11)
	v_pk_fma_f32 v[56:57], v[56:57], v[88:89], v[184:185]
	v_pk_fma_f32 v[58:59], v[58:59], v[90:91], v[186:187]
	global_store_dwordx4 v[236:237], v[56:59], off offset:64
	s_waitcnt vmcnt(11)
	v_pk_fma_f32 v[52:53], v[52:53], v[84:85], v[188:189]
	v_pk_fma_f32 v[54:55], v[54:55], v[86:87], v[190:191]
	global_store_dwordx4 v[236:237], v[52:55], off offset:512
	s_waitcnt vmcnt(11)
	v_pk_fma_f32 v[48:49], v[48:49], v[80:81], v[192:193]
	v_pk_fma_f32 v[50:51], v[50:51], v[82:83], v[194:195]
	global_store_dwordx4 v[236:237], v[48:51], off offset:576
	v_add_co_u32_e32 v212, vcc, 0xa0000, v178
	s_nop 1
	v_addc_co_u32_e32 v213, vcc, 0, v179, vcc
	global_load_dwordx4 v[180:183], v[212:213], off
	global_load_dwordx4 v[184:187], v[212:213], off offset:64
	global_load_dwordx4 v[188:191], v[212:213], off offset:512
	global_load_dwordx4 v[192:195], v[212:213], off offset:576
	v_add_co_u32_e32 v236, vcc, 0x90000, v154
	s_nop 1
	v_addc_co_u32_e32 v237, vcc, 0, v155, vcc
	s_waitcnt vmcnt(11)
;   __device__ __forceinline__ void operator()(const f32x4 (&acc)[2][2][4][2], const pg8::Unit& u, int wr, int wc, int fr, int fq) const {
;     ...
;           float* xb;
;           { int b_ = row >= TPB ? 1 : 0; int u_ = row - b_ * TPB;
;             xb = (u_ < CTX) ? xctx + (size_t)(b_ * CTX + u_) * D : xout + ((size_t)b_ * SEQ + (u_ - CTX)) * D; }
;           const float* xr = (xb >= xout && xb < xout + (size_t)2 * SEQ * D) ? xin + (xb - xout) : xb;
; #pragma unroll
;           for (int bj = 0; bj < 2; ++bj)
; #pragma unroll
;             for (int n = 0; n < 2; ++n) {
;               int cc = u.pn * 256 + bj * 128 + wc * 32 + n * 16 + fq * 4;
;               const float4 gs = gsv[bj][n];
;               float4 xv = *(const float4*)(xr + cc);
;               f32x4 a = acc[ai][bj][m][n];
;               xv.x += gs.x * a[0]; xv.y += gs.y * a[1]; xv.z += gs.z * a[2]; xv.w += gs.w * a[3];
;               *(float4*)(xb + cc) = xv;
	v_pk_fma_f32 v[44:45], v[44:45], v[96:97], v[196:197]
	v_pk_fma_f32 v[46:47], v[46:47], v[98:99], v[198:199]
	global_store_dwordx4 v[236:237], v[44:47], off
	s_waitcnt vmcnt(11)
	v_pk_fma_f32 v[40:41], v[40:41], v[88:89], v[200:201]
	v_pk_fma_f32 v[42:43], v[42:43], v[90:91], v[202:203]
	global_store_dwordx4 v[236:237], v[40:43], off offset:64
	s_waitcnt vmcnt(11)
	v_pk_fma_f32 v[36:37], v[36:37], v[84:85], v[204:205]
	v_pk_fma_f32 v[38:39], v[38:39], v[86:87], v[206:207]
	global_store_dwordx4 v[236:237], v[36:39], off offset:512
	s_waitcnt vmcnt(11)
	v_pk_fma_f32 v[32:33], v[32:33], v[80:81], v[208:209]
	v_pk_fma_f32 v[34:35], v[34:35], v[82:83], v[210:211]
	global_store_dwordx4 v[236:237], v[32:35], off offset:576
	v_add_co_u32_e32 v212, vcc, 0xb0000, v178
	s_nop 1
	v_addc_co_u32_e32 v213, vcc, 0, v179, vcc
	global_load_dwordx4 v[196:199], v[212:213], off
	global_load_dwordx4 v[200:203], v[212:213], off offset:64
	global_load_dwordx4 v[204:207], v[212:213], off offset:512
	global_load_dwordx4 v[208:211], v[212:213], off offset:576
	v_add_co_u32_e32 v236, vcc, 0xa0000, v154
	s_nop 1
	v_addc_co_u32_e32 v237, vcc, 0, v155, vcc
	s_waitcnt vmcnt(11)
	v_pk_fma_f32 v[28:29], v[28:29], v[96:97], v[180:181]
	v_pk_fma_f32 v[30:31], v[30:31], v[98:99], v[182:183]
	global_store_dwordx4 v[236:237], v[28:31], off
	s_waitcnt vmcnt(11)
	v_pk_fma_f32 v[24:25], v[24:25], v[88:89], v[184:185]
	v_pk_fma_f32 v[26:27], v[26:27], v[90:91], v[186:187]
	global_store_dwordx4 v[236:237], v[24:27], off offset:64
	s_waitcnt vmcnt(11)
	v_pk_fma_f32 v[20:21], v[20:21], v[84:85], v[188:189]
	v_pk_fma_f32 v[22:23], v[22:23], v[86:87], v[190:191]
	global_store_dwordx4 v[236:237], v[20:23], off offset:512
	s_waitcnt vmcnt(11)
	v_pk_fma_f32 v[16:17], v[16:17], v[80:81], v[192:193]
	v_pk_fma_f32 v[18:19], v[18:19], v[82:83], v[194:195]
	global_store_dwordx4 v[236:237], v[16:19], off offset:576
	v_add_co_u32_e32 v236, vcc, 0xb0000, v154
	s_nop 1
	v_addc_co_u32_e32 v237, vcc, 0, v155, vcc
	s_waitcnt vmcnt(7)
	v_pk_fma_f32 v[12:13], v[12:13], v[96:97], v[196:197]
	v_pk_fma_f32 v[14:15], v[14:15], v[98:99], v[198:199]
	global_store_dwordx4 v[236:237], v[12:15], off
	s_waitcnt vmcnt(7)
	v_pk_fma_f32 v[8:9], v[8:9], v[88:89], v[200:201]
	v_pk_fma_f32 v[10:11], v[10:11], v[90:91], v[202:203]
	global_store_dwordx4 v[236:237], v[8:11], off offset:64
	s_waitcnt vmcnt(7)
	v_pk_fma_f32 v[4:5], v[4:5], v[84:85], v[204:205]
	v_pk_fma_f32 v[6:7], v[6:7], v[86:87], v[206:207]
	global_store_dwordx4 v[236:237], v[4:7], off offset:512
	s_waitcnt vmcnt(7)
	v_pk_fma_f32 v[0:1], v[0:1], v[80:81], v[208:209]
	v_pk_fma_f32 v[2:3], v[2:3], v[82:83], v[210:211]
	global_store_dwordx4 v[236:237], v[0:3], off offset:576
	s_nop 1
	v_add_u32_e32 v128, s8, v159
	v_cmp_lt_i32_e32 vcc, s2, v128
	s_nop 1
	v_cndmask_b32_e32 v129, 0, v228, vcc
	v_add_u32_e32 v132, v129, v128
	v_cmp_lt_i32_e64 s[42:43], s81, v132
	s_and_saveexec_b64 s[2:3], s[42:43]
	s_xor_b64 s[2:3], exec, s[2:3]
	v_cndmask_b32_e32 v128, 0, v230, vcc
	s_movk_i32 s4, 0xff00
	v_add3_u32 v166, v132, v128, s4
	v_mov_b64_e32 v[128:129], v[166:167]
	s_or_saveexec_b64 s[4:5], s[2:3]
	v_mov_b64_e32 v[130:131], s[44:45]
	s_xor_b64 exec, exec, s[4:5]
	v_cndmask_b32_e32 v128, 0, v229, vcc
	v_add_u32_e32 v128, v132, v128
	v_ashrrev_i32_e32 v129, 31, v128
	v_mov_b64_e32 v[130:131], s[48:49]
	s_or_b64 exec, exec, s[4:5]
	v_lshlrev_b64 v[128:129], 12, v[128:129]
	v_lshl_add_u64 v[128:129], v[130:131], 0, v[128:129]
	v_cmp_le_u64_e32 vcc, s[44:45], v[128:129]
	v_cmp_gt_u64_e64 s[42:43], s[56:57], v[128:129]
	s_and_b64 vcc, vcc, s[42:43]
	v_subrev_co_u32_e64 v130, s[42:43], s44, v128
	v_mov_b32_e32 v131, s45
	s_nop 0
	v_subb_co_u32_e64 v131, s[42:43], v129, v131, s[42:43]
	v_lshl_add_u64 v[130:131], s[44:45], 0, v[130:131]
	v_cndmask_b32_e32 v131, v129, v131, vcc
	v_cndmask_b32_e32 v130, v128, v130, vcc
	v_lshl_add_u64 v[132:133], v[130:131], 0, v[152:153]
	v_lshl_add_u64 v[134:135], v[128:129], 0, v[152:153]
	s_movk_i32 s2, 0x20ff
	s_nop 1
	v_add_u32_e32 v112, s8, v160
	v_cmp_lt_i32_e32 vcc, s2, v112
	s_nop 1
	v_cndmask_b32_e32 v113, 0, v228, vcc
	v_add_u32_e32 v116, v113, v112
	v_cmp_lt_i32_e64 s[42:43], s81, v116
	s_and_saveexec_b64 s[2:3], s[42:43]
	s_xor_b64 s[2:3], exec, s[2:3]
	v_cndmask_b32_e32 v112, 0, v230, vcc
	s_movk_i32 s4, 0xff00
	v_add3_u32 v166, v116, v112, s4
	v_mov_b64_e32 v[112:113], v[166:167]
	s_or_saveexec_b64 s[4:5], s[2:3]
	v_mov_b64_e32 v[114:115], s[44:45]
	s_xor_b64 exec, exec, s[4:5]
	v_cndmask_b32_e32 v112, 0, v229, vcc
	v_add_u32_e32 v112, v116, v112
	v_ashrrev_i32_e32 v113, 31, v112
	v_mov_b64_e32 v[114:115], s[48:49]
	s_or_b64 exec, exec, s[4:5]
	v_lshlrev_b64 v[112:113], 12, v[112:113]
	v_lshl_add_u64 v[112:113], v[114:115], 0, v[112:113]
	v_cmp_le_u64_e32 vcc, s[44:45], v[112:113]
	v_cmp_gt_u64_e64 s[42:43], s[56:57], v[112:113]
	s_and_b64 vcc, vcc, s[42:43]
	v_subrev_co_u32_e64 v114, s[42:43], s44, v112
	v_mov_b32_e32 v115, s45
	s_nop 0
	v_subb_co_u32_e64 v115, s[42:43], v113, v115, s[42:43]
	v_lshl_add_u64 v[114:115], s[44:45], 0, v[114:115]
	v_cndmask_b32_e32 v115, v113, v115, vcc
	v_cndmask_b32_e32 v114, v112, v114, vcc
	v_lshl_add_u64 v[116:117], v[114:115], 0, v[152:153]
	v_lshl_add_u64 v[118:119], v[112:113], 0, v[152:153]
	s_movk_i32 s2, 0x20ff
	s_nop 1
	v_add_u32_e32 v92, s8, v161
	v_cmp_lt_i32_e32 vcc, s2, v92
	s_nop 1
	v_cndmask_b32_e32 v93, 0, v228, vcc
	v_add_u32_e32 v100, v93, v92
;   __device__ __forceinline__ void operator()(const f32x4 (&acc)[2][2][4][2], const pg8::Unit& u, int wr, int wc, int fr, int fq) const {
;     ...
;           float* xb;
;           { int b_ = row >= TPB ? 1 : 0; int u_ = row - b_ * TPB;
;             xb = (u_ < CTX) ? xctx + (size_t)(b_ * CTX + u_) * D : xout + ((size_t)b_ * SEQ + (u_ - CTX)) * D; }
;           const float* xr = (xb >= xout && xb < xout + (size_t)2 * SEQ * D) ? xin + (xb - xout) : xb;
; #pragma unroll
;           for (int bj = 0; bj < 2; ++bj)
; #pragma unroll
;             for (int n = 0; n < 2; ++n) {
;               int cc = u.pn * 256 + bj * 128 + wc * 32 + n * 16 + fq * 4;
;               const float4 gs = gsv[bj][n];
;               float4 xv = *(const float4*)(xr + cc);
;               f32x4 a = acc[ai][bj][m][n];
;               xv.x += gs.x * a[0]; xv.y += gs.y * a[1]; xv.z += gs.z * a[2]; xv.w += gs.w * a[3];
;               *(float4*)(xb + cc) = xv;
	v_cmp_lt_i32_e64 s[42:43], s81, v100
	s_and_saveexec_b64 s[2:3], s[42:43]
	s_xor_b64 s[2:3], exec, s[2:3]
	v_cndmask_b32_e32 v92, 0, v230, vcc
	s_movk_i32 s4, 0xff00
	v_add3_u32 v166, v100, v92, s4
	v_mov_b64_e32 v[92:93], v[166:167]
	s_or_saveexec_b64 s[4:5], s[2:3]
	v_mov_b64_e32 v[94:95], s[44:45]
	s_xor_b64 exec, exec, s[4:5]
	v_cndmask_b32_e32 v92, 0, v229, vcc
	v_add_u32_e32 v92, v100, v92
	v_ashrrev_i32_e32 v93, 31, v92
	v_mov_b64_e32 v[94:95], s[48:49]
	s_or_b64 exec, exec, s[4:5]
	v_lshlrev_b64 v[92:93], 12, v[92:93]
	v_lshl_add_u64 v[92:93], v[94:95], 0, v[92:93]
	v_cmp_le_u64_e32 vcc, s[44:45], v[92:93]
	v_cmp_gt_u64_e64 s[42:43], s[56:57], v[92:93]
	s_and_b64 vcc, vcc, s[42:43]
	v_subrev_co_u32_e64 v94, s[42:43], s44, v92
	v_mov_b32_e32 v95, s45
	s_nop 0
	v_subb_co_u32_e64 v95, s[42:43], v93, v95, s[42:43]
	v_lshl_add_u64 v[94:95], s[44:45], 0, v[94:95]
	v_cndmask_b32_e32 v95, v93, v95, vcc
	v_cndmask_b32_e32 v94, v92, v94, vcc
	v_lshl_add_u64 v[100:101], v[94:95], 0, v[152:153]
	v_lshl_add_u64 v[102:103], v[92:93], 0, v[152:153]
	s_movk_i32 s2, 0x20ff
	s_nop 1
	v_add_u32_e32 v64, 0x80, v171
	v_cmp_lt_i32_e32 vcc, s2, v64
	s_nop 1
	v_cndmask_b32_e32 v65, 0, v228, vcc
	v_add_u32_e32 v68, v65, v64
	v_cmp_lt_i32_e64 s[42:43], s81, v68
	s_and_saveexec_b64 s[2:3], s[42:43]
	s_xor_b64 s[2:3], exec, s[2:3]
	v_cndmask_b32_e32 v64, 0, v230, vcc
	s_movk_i32 s4, 0xff00
	v_add3_u32 v166, v68, v64, s4
	v_mov_b64_e32 v[64:65], v[166:167]
	s_or_saveexec_b64 s[4:5], s[2:3]
	v_mov_b64_e32 v[66:67], s[44:45]
	s_xor_b64 exec, exec, s[4:5]
	v_cndmask_b32_e32 v64, 0, v229, vcc
	v_add_u32_e32 v64, v68, v64
	v_ashrrev_i32_e32 v65, 31, v64
	v_mov_b64_e32 v[66:67], s[48:49]
	s_or_b64 exec, exec, s[4:5]
	v_lshlrev_b64 v[64:65], 12, v[64:65]
	v_lshl_add_u64 v[64:65], v[66:67], 0, v[64:65]
	v_cmp_le_u64_e32 vcc, s[44:45], v[64:65]
	v_cmp_gt_u64_e64 s[42:43], s[56:57], v[64:65]
	s_and_b64 vcc, vcc, s[42:43]
	v_subrev_co_u32_e64 v66, s[42:43], s44, v64
	v_mov_b32_e32 v67, s45
	s_nop 0
	v_subb_co_u32_e64 v67, s[42:43], v65, v67, s[42:43]
	v_lshl_add_u64 v[66:67], s[44:45], 0, v[66:67]
	v_cndmask_b32_e32 v67, v65, v67, vcc
	v_cndmask_b32_e32 v66, v64, v66, vcc
	v_lshl_add_u64 v[68:69], v[66:67], 0, v[152:153]
	v_lshl_add_u64 v[70:71], v[64:65], 0, v[152:153]
	s_movk_i32 s2, 0x20ff
	s_nop 1
	v_add_u32_e32 v48, 0x90, v171
	v_cmp_lt_i32_e32 vcc, s2, v48
	s_nop 1
	v_cndmask_b32_e32 v49, 0, v228, vcc
	v_add_u32_e32 v52, v49, v48
	v_cmp_lt_i32_e64 s[42:43], s81, v52
	s_and_saveexec_b64 s[2:3], s[42:43]
	s_xor_b64 s[2:3], exec, s[2:3]
	v_cndmask_b32_e32 v48, 0, v230, vcc
	s_movk_i32 s4, 0xff00
	v_add3_u32 v166, v52, v48, s4
	v_mov_b64_e32 v[48:49], v[166:167]
	s_or_saveexec_b64 s[4:5], s[2:3]
	v_mov_b64_e32 v[50:51], s[44:45]
	s_xor_b64 exec, exec, s[4:5]
	v_cndmask_b32_e32 v48, 0, v229, vcc
	v_add_u32_e32 v48, v52, v48
	v_ashrrev_i32_e32 v49, 31, v48
	v_mov_b64_e32 v[50:51], s[48:49]
	s_or_b64 exec, exec, s[4:5]
	v_lshlrev_b64 v[48:49], 12, v[48:49]
	v_lshl_add_u64 v[48:49], v[50:51], 0, v[48:49]
	v_cmp_le_u64_e32 vcc, s[44:45], v[48:49]
	v_cmp_gt_u64_e64 s[42:43], s[56:57], v[48:49]
	s_and_b64 vcc, vcc, s[42:43]
	v_subrev_co_u32_e64 v50, s[42:43], s44, v48
	v_mov_b32_e32 v51, s45
	s_nop 0
	v_subb_co_u32_e64 v51, s[42:43], v49, v51, s[42:43]
	v_lshl_add_u64 v[50:51], s[44:45], 0, v[50:51]
	v_cndmask_b32_e32 v51, v49, v51, vcc
	v_cndmask_b32_e32 v50, v48, v50, vcc
	v_lshl_add_u64 v[52:53], v[50:51], 0, v[152:153]
	v_lshl_add_u64 v[54:55], v[48:49], 0, v[152:153]
	s_movk_i32 s2, 0x20ff
	s_nop 1
	v_add_u32_e32 v32, 0xa0, v171
	v_cmp_lt_i32_e32 vcc, s2, v32
	s_nop 1
	v_cndmask_b32_e32 v33, 0, v228, vcc
	v_add_u32_e32 v36, v33, v32
	v_cmp_lt_i32_e64 s[42:43], s81, v36
	s_and_saveexec_b64 s[2:3], s[42:43]
	s_xor_b64 s[2:3], exec, s[2:3]
	v_cndmask_b32_e32 v32, 0, v230, vcc
	s_movk_i32 s4, 0xff00
	v_add3_u32 v166, v36, v32, s4
	v_mov_b64_e32 v[32:33], v[166:167]
	s_or_saveexec_b64 s[4:5], s[2:3]
	v_mov_b64_e32 v[34:35], s[44:45]
	s_xor_b64 exec, exec, s[4:5]
	v_cndmask_b32_e32 v32, 0, v229, vcc
	v_add_u32_e32 v32, v36, v32
	v_ashrrev_i32_e32 v33, 31, v32
	v_mov_b64_e32 v[34:35], s[48:49]
	s_or_b64 exec, exec, s[4:5]
	v_lshlrev_b64 v[32:33], 12, v[32:33]
	v_lshl_add_u64 v[32:33], v[34:35], 0, v[32:33]
	v_cmp_le_u64_e32 vcc, s[44:45], v[32:33]
	v_cmp_gt_u64_e64 s[42:43], s[56:57], v[32:33]
	s_and_b64 vcc, vcc, s[42:43]
	v_subrev_co_u32_e64 v34, s[42:43], s44, v32
	v_mov_b32_e32 v35, s45
	s_nop 0
	v_subb_co_u32_e64 v35, s[42:43], v33, v35, s[42:43]
	v_lshl_add_u64 v[34:35], s[44:45], 0, v[34:35]
	v_cndmask_b32_e32 v35, v33, v35, vcc
	v_cndmask_b32_e32 v34, v32, v34, vcc
	v_lshl_add_u64 v[36:37], v[34:35], 0, v[152:153]
	v_lshl_add_u64 v[38:39], v[32:33], 0, v[152:153]
	s_movk_i32 s2, 0x20ff
	s_nop 1
	v_add_u32_e32 v16, 0xb0, v171
	v_cmp_lt_i32_e32 vcc, s2, v16
	s_nop 1
	v_cndmask_b32_e32 v17, 0, v228, vcc
	v_add_u32_e32 v20, v17, v16
	v_cmp_lt_i32_e64 s[42:43], s81, v20
	s_and_saveexec_b64 s[2:3], s[42:43]
	s_xor_b64 s[2:3], exec, s[2:3]
	v_cndmask_b32_e32 v16, 0, v230, vcc
	s_movk_i32 s4, 0xff00
	v_add3_u32 v166, v20, v16, s4
	v_mov_b64_e32 v[16:17], v[166:167]
	s_or_saveexec_b64 s[4:5], s[2:3]
	v_mov_b64_e32 v[18:19], s[44:45]
	s_xor_b64 exec, exec, s[4:5]
	s_cbranch_execz .LBB0_339
	v_cndmask_b32_e32 v16, 0, v229, vcc
	v_add_u32_e32 v16, v20, v16
	v_ashrrev_i32_e32 v17, 31, v16
	v_mov_b64_e32 v[18:19], s[48:49]
	s_branch .LBB0_339

;   __device__ __forceinline__ void operator()(const f32x4 (&acc)[2][2][4][2], const pg8::Unit& u, int wr, int wc, int fr, int fq) const {
;     ...
;           float* xb;
;           { int b_ = row >= TPB ? 1 : 0; int u_ = row - b_ * TPB;
;             xb = (u_ < CTX) ? xctx + (size_t)(b_ * CTX + u_) * D : xout + ((size_t)b_ * SEQ + (u_ - CTX)) * D; }
;           const float* xr = (xb >= xout && xb < xout + (size_t)2 * SEQ * D) ? xin + (xb - xout) : xb;
; #pragma unroll
;           for (int bj = 0; bj < 2; ++bj)
; #pragma unroll
;             for (int n = 0; n < 2; ++n) {
;               int cc = u.pn * 256 + bj * 128 + wc * 32 + n * 16 + fq * 4;
;               const float4 gs = gsv[bj][n];
;               float4 xv = *(const float4*)(xr + cc);
;               f32x4 a = acc[ai][bj][m][n];
;               xv.x += gs.x * a[0]; xv.y += gs.y * a[1]; xv.z += gs.z * a[2]; xv.w += gs.w * a[3];
;               *(float4*)(xb + cc) = xv;
.LBB0_833:
	s_or_b64 exec, exec, s[4:5]
	v_lshlrev_b64 v[16:17], 12, v[16:17]
	v_lshl_add_u64 v[16:17], v[18:19], 0, v[16:17]
	v_cmp_le_u64_e32 vcc, s[48:49], v[16:17]
	v_cmp_gt_u64_e64 s[42:43], s[58:59], v[16:17]
	s_and_b64 vcc, vcc, s[42:43]
	v_subrev_co_u32_e64 v18, s[42:43], s48, v16
	v_mov_b32_e32 v19, s49
	s_nop 0
	v_subb_co_u32_e64 v19, s[42:43], v17, v19, s[42:43]
	v_lshl_add_u64 v[18:19], s[56:57], 0, v[18:19]
	v_cndmask_b32_e32 v19, v17, v19, vcc
	v_cndmask_b32_e32 v18, v16, v18, vcc
	v_lshl_add_u64 v[20:21], v[18:19], 0, v[134:135]
	v_lshl_add_u64 v[22:23], v[16:17], 0, v[134:135]
	s_and_b64 vcc, exec, s[40:41]
	s_mov_b32 s38, s36
	s_mov_b32 s39, s37
	s_mov_b64 s[6:7], s[44:45]
	s_mov_b64 s[4:5], s[60:61]
	s_cbranch_vccnz .LBB0_878

; #define PG8_STAGE(bufoff, gbase, voff) do { _Pragma("unroll") for (int _i = 0; _i < 2; ++_i) \
;         __builtin_amdgcn_global_load_lds((const unsigned*)((const char*)(gbase) + (voff)[_i]), (PG8_LAS unsigned*)(lds + (bufoff) + ldsw + _i * 8192), 16, 0, 0); } while (0)
; #define PG8_LDA(dst, b, h) do { _Pragma("unroll") for (int m = 0; m < 4; ++m) _Pragma("unroll") for (int k = 0; k < 2; ++k) dst[m][k] = *(const PG8_LAS bf16x8*)(lds + PG8_SA(b, h) + aoff + m * 2048 + k * 1024); } while (0)
; #define PG8_LDB(dst, b, h) do { _Pragma("unroll") for (int n = 0; n < 2; ++n) _Pragma("unroll") for (int k = 0; k < 2; ++k) dst[n][k] = *(const PG8_LAS bf16x8*)(lds + PG8_SB(b, h) + boff + n * 2048 + k * 1024); } while (0)
; #define PG8_MMA(ai, bj, At, Bt) do { __builtin_amdgcn_s_setprio(1); _Pragma("unroll") for (int m = 0; m < 4; ++m) _Pragma("unroll") for (int n = 0; n < 2; ++n) _Pragma("unroll") for (int k = 0; k < 2; ++k) \
;         acc[ai][bj][m][n] = __builtin_amdgcn_mfma_f32_16x16x32_bf16(Bt[n][k], At[m][k], acc[ai][bj][m][n], 0, 0, 0); __builtin_amdgcn_s_setprio(0); } while (0)
; template <class Epi>
; __device__ __forceinline__ void gemm_phase(PG8_LAS unsigned char* lds, const Gemm g, const Sched& S, const Epi& E) {
;     ...
;         const char* nA = has_next ? (const char*)g.A + (size_t)nxt.pm * tsA : cA; const char* nB = has_next ? (const char*)g.Bt + (size_t)nxt.pn * tsB : cB;
;         for (int t = 0; t < nt; t += 2) {
;             const bool last = (t == nt - 2);
;             const char* a1 = cA + (size_t)(t + 1) * kstep;
;             const char* a2 = last ? nA : cA + (size_t)(t + 2) * kstep; const char* b2 = last ? nB : cB + (size_t)(t + 2) * kstep;
;             const char* a3 = a2 + kstep; const char* b3 = b2 + kstep;
;             PG8_LDB(B0, 0, 0); PG8_SCHED; PG8_LDA(At, 0, 0); PG8_STAGE(PG8_SA(1, 1), a1 + hsA, voffA);
;             PG8_WAIT_L(8); PG8_BAR; PG8_WAIT_L(0); PG8_MMA(0, 0, At, B0); PG8_BAR; PG8_SCHED;
;             PG8_LDB(B1, 0, 1); PG8_STAGE(PG8_SB(0, 0), b2, voffB);
;             PG8_BAR; PG8_WAIT_L(0); PG8_MMA(0, 1, At, B1); PG8_BAR;
;             PG8_LDA(At, 0, 1); PG8_STAGE(PG8_SA(0, 0), a2, voffA);
;             PG8_BAR; PG8_WAIT_L(0); PG8_MMA(1, 0, At, B0); PG8_BAR; PG8_SCHED;
;             PG8_STAGE(PG8_SB(0, 1), b2 + hsB, voffB);
;             PG8_WAIT_V(6); PG8_BAR; PG8_MMA(1, 1, At, B1); PG8_BAR;
.LBB0_845:
	s_add_u32 s6, s4, 0x100
	s_addc_u32 s7, s5, 0
	s_add_i32 s43, 0, 0x10000
	v_add_u32_e32 v140, s43, v159
	ds_read_b128 v[128:131], v140
	ds_read_b128 v[132:135], v140 offset:1024
	ds_read_b128 v[136:139], v140 offset:2048
	ds_read_b128 v[140:143], v140 offset:3072
	s_cmp_eq_u32 s42, 40
	s_cselect_b32 s11, s61, s7
	s_cselect_b32 s10, s60, s6
	s_cselect_b32 s9, s45, s3
	s_cselect_b32 s8, s44, s2
	v_lshl_add_u64 v[156:157], s[4:5], 0, v[148:149]
	s_add_i32 m0, s19, 0xc000
	ds_read_b128 v[152:155], v171
	ds_read_b128 v[180:183], v171 offset:1024
	ds_read_b128 v[184:187], v171 offset:2048
	ds_read_b128 v[188:191], v171 offset:3072
	ds_read_b128 v[192:195], v171 offset:4096
	ds_read_b128 v[196:199], v171 offset:5120
	ds_read_b128 v[200:203], v171 offset:6144
	ds_read_b128 v[204:207], v171 offset:7168
	global_load_lds_dwordx4 v[156:157], off
	v_lshl_add_u64 v[156:157], s[4:5], 0, v[150:151]
	s_add_i32 m0, s19, 0xe000
	s_nop 0
	global_load_lds_dwordx4 v[156:157], off
	s_waitcnt lgkmcnt(8)
	s_barrier
	s_waitcnt lgkmcnt(0)
	s_setprio 1
	s_waitcnt lgkmcnt(0)
	v_mfma_f32_16x16x32_bf16 v[124:127], v[128:131], v[152:155], v[124:127]
	v_mfma_f32_16x16x32_bf16 v[120:123], v[136:139], v[152:155], v[120:123]
	v_mfma_f32_16x16x32_bf16 v[108:111], v[128:131], v[184:187], v[108:111]
	v_mfma_f32_16x16x32_bf16 v[104:107], v[136:139], v[184:187], v[104:107]
	v_mfma_f32_16x16x32_bf16 v[92:95], v[128:131], v[192:195], v[92:95]
	v_mfma_f32_16x16x32_bf16 v[88:91], v[136:139], v[192:195], v[88:91]
	v_mfma_f32_16x16x32_bf16 v[76:79], v[128:131], v[200:203], v[76:79]
	v_mfma_f32_16x16x32_bf16 v[72:75], v[136:139], v[200:203], v[72:75]
	v_mfma_f32_16x16x32_bf16 v[124:127], v[132:135], v[180:183], v[124:127]
	v_mfma_f32_16x16x32_bf16 v[120:123], v[140:143], v[180:183], v[120:123]
	v_mfma_f32_16x16x32_bf16 v[108:111], v[132:135], v[188:191], v[108:111]
	v_mfma_f32_16x16x32_bf16 v[104:107], v[140:143], v[188:191], v[104:107]
	v_mfma_f32_16x16x32_bf16 v[92:95], v[132:135], v[196:199], v[92:95]
	v_mfma_f32_16x16x32_bf16 v[88:91], v[140:143], v[196:199], v[88:91]
	v_mfma_f32_16x16x32_bf16 v[76:79], v[132:135], v[204:207], v[76:79]
	v_mfma_f32_16x16x32_bf16 v[72:75], v[140:143], v[204:207], v[72:75]
	s_setprio 0
	s_barrier
	s_add_i32 s62, 0, 0x14000
	v_add_u32_e32 v156, s62, v159
	s_add_i32 s4, s43, s18
	ds_read_b128 v[208:211], v156
	ds_read_b128 v[212:215], v156 offset:1024
	ds_read_b128 v[236:239], v156 offset:2048
	ds_read_b128 v[240:243], v156 offset:3072
	v_lshl_add_u64 v[156:157], s[8:9], 0, v[144:145]
	s_mov_b32 m0, s4
	v_lshl_add_u64 v[172:173], s[8:9], 0, v[146:147]
	global_load_lds_dwordx4 v[156:157], off
	s_add_i32 m0, s4, 0x2000
	s_nop 0
	global_load_lds_dwordx4 v[172:173], off
	s_barrier
	s_waitcnt lgkmcnt(0)
	s_setprio 1
	s_waitcnt lgkmcnt(0)
	v_mfma_f32_16x16x32_bf16 v[116:119], v[208:211], v[152:155], v[116:119]
	v_mfma_f32_16x16x32_bf16 v[112:115], v[236:239], v[152:155], v[112:115]
	v_mfma_f32_16x16x32_bf16 v[100:103], v[208:211], v[184:187], v[100:103]
	v_mfma_f32_16x16x32_bf16 v[96:99], v[236:239], v[184:187], v[96:99]
	v_mfma_f32_16x16x32_bf16 v[84:87], v[208:211], v[192:195], v[84:87]
	v_mfma_f32_16x16x32_bf16 v[80:83], v[236:239], v[192:195], v[80:83]
	v_mfma_f32_16x16x32_bf16 v[68:71], v[208:211], v[200:203], v[68:71]
	v_mfma_f32_16x16x32_bf16 v[64:67], v[236:239], v[200:203], v[64:67]
	v_mfma_f32_16x16x32_bf16 v[116:119], v[212:215], v[180:183], v[116:119]
	v_mfma_f32_16x16x32_bf16 v[112:115], v[240:243], v[180:183], v[112:115]
	v_mfma_f32_16x16x32_bf16 v[100:103], v[212:215], v[188:191], v[100:103]
	v_mfma_f32_16x16x32_bf16 v[96:99], v[240:243], v[188:191], v[96:99]
	v_mfma_f32_16x16x32_bf16 v[84:87], v[212:215], v[196:199], v[84:87]
	v_mfma_f32_16x16x32_bf16 v[80:83], v[240:243], v[196:199], v[80:83]
	v_mfma_f32_16x16x32_bf16 v[68:71], v[212:215], v[204:207], v[68:71]
	v_mfma_f32_16x16x32_bf16 v[64:67], v[240:243], v[204:207], v[64:67]
	s_setprio 0
	s_mov_b32 m0, s19
	v_lshl_add_u64 v[174:175], s[10:11], 0, v[144:145]
	s_barrier
	ds_read_b128 v[152:155], v171 offset:16384
	ds_read_b128 v[180:183], v171 offset:17408
	ds_read_b128 v[184:187], v171 offset:18432
	ds_read_b128 v[188:191], v171 offset:19456
	ds_read_b128 v[192:195], v171 offset:20480
	ds_read_b128 v[196:199], v171 offset:21504
	ds_read_b128 v[200:203], v171 offset:22528
	ds_read_b128 v[204:207], v171 offset:23552
	global_load_lds_dwordx4 v[174:175], off
	v_lshl_add_u64 v[244:245], s[10:11], 0, v[146:147]
	s_mov_b32 m0, s20
	s_nop 0
	global_load_lds_dwordx4 v[244:245], off
	s_barrier
	s_waitcnt lgkmcnt(0)
	s_setprio 1
	s_waitcnt lgkmcnt(0)
	v_mfma_f32_16x16x32_bf16 v[60:63], v[128:131], v[152:155], v[60:63]
	v_mfma_f32_16x16x32_bf16 v[56:59], v[136:139], v[152:155], v[56:59]
	v_mfma_f32_16x16x32_bf16 v[44:47], v[128:131], v[184:187], v[44:47]
	v_mfma_f32_16x16x32_bf16 v[40:43], v[136:139], v[184:187], v[40:43]
	v_mfma_f32_16x16x32_bf16 v[28:31], v[128:131], v[192:195], v[28:31]
	v_mfma_f32_16x16x32_bf16 v[24:27], v[136:139], v[192:195], v[24:27]
	v_mfma_f32_16x16x32_bf16 v[12:15], v[128:131], v[200:203], v[12:15]
	v_mfma_f32_16x16x32_bf16 v[8:11], v[136:139], v[200:203], v[8:11]
	v_mfma_f32_16x16x32_bf16 v[60:63], v[132:135], v[180:183], v[60:63]
	v_mfma_f32_16x16x32_bf16 v[56:59], v[140:143], v[180:183], v[56:59]
	v_mfma_f32_16x16x32_bf16 v[44:47], v[132:135], v[188:191], v[44:47]
	v_mfma_f32_16x16x32_bf16 v[40:43], v[140:143], v[188:191], v[40:43]
	v_mfma_f32_16x16x32_bf16 v[28:31], v[132:135], v[196:199], v[28:31]
	v_mfma_f32_16x16x32_bf16 v[24:27], v[140:143], v[196:199], v[24:27]
	v_mfma_f32_16x16x32_bf16 v[12:15], v[132:135], v[204:207], v[12:15]
	v_mfma_f32_16x16x32_bf16 v[8:11], v[140:143], v[204:207], v[8:11]
	s_setprio 0
	s_barrier
; #define PG8_STAGE(bufoff, gbase, voff) do { _Pragma("unroll") for (int _i = 0; _i < 2; ++_i) \
;         __builtin_amdgcn_global_load_lds((const unsigned*)((const char*)(gbase) + (voff)[_i]), (PG8_LAS unsigned*)(lds + (bufoff) + ldsw + _i * 8192), 16, 0, 0); } while (0)
; #define PG8_LDA(dst, b, h) do { _Pragma("unroll") for (int m = 0; m < 4; ++m) _Pragma("unroll") for (int k = 0; k < 2; ++k) dst[m][k] = *(const PG8_LAS bf16x8*)(lds + PG8_SA(b, h) + aoff + m * 2048 + k * 1024); } while (0)
; #define PG8_LDB(dst, b, h) do { _Pragma("unroll") for (int n = 0; n < 2; ++n) _Pragma("unroll") for (int k = 0; k < 2; ++k) dst[n][k] = *(const PG8_LAS bf16x8*)(lds + PG8_SB(b, h) + boff + n * 2048 + k * 1024); } while (0)
; #define PG8_MMA(ai, bj, At, Bt) do { __builtin_amdgcn_s_setprio(1); _Pragma("unroll") for (int m = 0; m < 4; ++m) _Pragma("unroll") for (int n = 0; n < 2; ++n) _Pragma("unroll") for (int k = 0; k < 2; ++k) \
;         acc[ai][bj][m][n] = __builtin_amdgcn_mfma_f32_16x16x32_bf16(Bt[n][k], At[m][k], acc[ai][bj][m][n], 0, 0, 0); __builtin_amdgcn_s_setprio(0); } while (0)
; #define PG8_WAIT_V(n) asm volatile("s_waitcnt vmcnt(" #n ")" ::: "memory")
; #define PG8_WAIT_L(n) asm volatile("s_waitcnt lgkmcnt(" #n ")" ::: "memory")
; #define PG8_BAR __builtin_amdgcn_s_barrier()
; #define PG8_SCHED __builtin_amdgcn_sched_barrier(0)
; template <class Epi>
; __device__ __forceinline__ void gemm_phase(PG8_LAS unsigned char* lds, const Gemm g, const Sched& S, const Epi& E) {
;     ...
;             PG8_BAR; PG8_WAIT_L(0); PG8_MMA(1, 0, At, B0); PG8_BAR; PG8_SCHED;
;             PG8_STAGE(PG8_SB(0, 1), b2 + hsB, voffB);
;             PG8_WAIT_V(6); PG8_BAR; PG8_MMA(1, 1, At, B1); PG8_BAR;
;             PG8_LDB(B0, 1, 0); PG8_SCHED; PG8_LDA(At, 1, 0); PG8_STAGE(PG8_SA(0, 1), a2 + hsA, voffA);
;             PG8_WAIT_L(8); PG8_BAR; PG8_WAIT_L(0); PG8_MMA(0, 0, At, B0); PG8_BAR; PG8_SCHED;
;             PG8_LDB(B1, 1, 1); PG8_STAGE(PG8_SB(1, 0), b3, voffB);
;             PG8_BAR; PG8_WAIT_L(0); PG8_MMA(0, 1, At, B1); PG8_BAR;
;             PG8_LDA(At, 1, 1); PG8_STAGE(PG8_SA(1, 0), a3, voffA);
;             PG8_BAR; PG8_WAIT_L(0); PG8_MMA(1, 0, At, B0); PG8_BAR; PG8_SCHED;
	s_add_u32 s4, s8, 0xb0000
	s_addc_u32 s5, s9, 0
	s_add_i32 s43, s62, s18
	v_lshl_add_u64 v[128:129], s[4:5], 0, v[144:145]
	s_mov_b32 m0, s43
	s_nop 0
	global_load_lds_dwordx4 v[128:129], off
	v_lshl_add_u64 v[128:129], s[4:5], 0, v[146:147]
	s_add_i32 m0, s43, 0x2000
	s_nop 0
	global_load_lds_dwordx4 v[128:129], off
	s_waitcnt vmcnt(6)
	s_barrier
	s_setprio 1
	v_mfma_f32_16x16x32_bf16 v[52:55], v[208:211], v[152:155], v[52:55]
	v_mfma_f32_16x16x32_bf16 v[48:51], v[236:239], v[152:155], v[48:51]
	v_mfma_f32_16x16x32_bf16 v[36:39], v[208:211], v[184:187], v[36:39]
	v_mfma_f32_16x16x32_bf16 v[32:35], v[236:239], v[184:187], v[32:35]
	v_mfma_f32_16x16x32_bf16 v[20:23], v[208:211], v[192:195], v[20:23]
	v_mfma_f32_16x16x32_bf16 v[16:19], v[236:239], v[192:195], v[16:19]
	v_mfma_f32_16x16x32_bf16 v[4:7], v[208:211], v[200:203], v[4:7]
	v_mfma_f32_16x16x32_bf16 v[0:3], v[236:239], v[200:203], v[0:3]
	v_mfma_f32_16x16x32_bf16 v[52:55], v[212:215], v[180:183], v[52:55]
	v_mfma_f32_16x16x32_bf16 v[48:51], v[240:243], v[180:183], v[48:51]
	v_mfma_f32_16x16x32_bf16 v[36:39], v[212:215], v[188:191], v[36:39]
	v_mfma_f32_16x16x32_bf16 v[32:35], v[240:243], v[188:191], v[32:35]
	v_mfma_f32_16x16x32_bf16 v[20:23], v[212:215], v[196:199], v[20:23]
	v_mfma_f32_16x16x32_bf16 v[16:19], v[240:243], v[196:199], v[16:19]
	v_mfma_f32_16x16x32_bf16 v[4:7], v[212:215], v[204:207], v[4:7]
	v_mfma_f32_16x16x32_bf16 v[0:3], v[240:243], v[204:207], v[0:3]
	s_setprio 0
	s_add_i32 s43, 0, 0x18000
	v_add_u32_e32 v140, s43, v159
	s_barrier
	ds_read_b128 v[128:131], v140
	ds_read_b128 v[132:135], v140 offset:1024
	ds_read_b128 v[136:139], v140 offset:2048
	ds_read_b128 v[140:143], v140 offset:3072
	s_add_u32 s4, s10, 0xb0000
	s_addc_u32 s5, s11, 0
	s_mov_b32 m0, s21
	v_lshl_add_u64 v[208:209], s[4:5], 0, v[144:145]
	ds_read_b128 v[152:155], v171 offset:32768
	ds_read_b128 v[180:183], v171 offset:33792
	ds_read_b128 v[184:187], v171 offset:34816
	ds_read_b128 v[188:191], v171 offset:35840
	ds_read_b128 v[192:195], v171 offset:36864
	ds_read_b128 v[196:199], v171 offset:37888
	ds_read_b128 v[200:203], v171 offset:38912
	ds_read_b128 v[204:207], v171 offset:39936
	global_load_lds_dwordx4 v[208:209], off
	v_lshl_add_u64 v[208:209], s[4:5], 0, v[146:147]
	s_mov_b32 m0, s22
	s_nop 0
	global_load_lds_dwordx4 v[208:209], off
	s_waitcnt lgkmcnt(8)
	s_barrier
	s_waitcnt lgkmcnt(0)
	s_setprio 1
	s_waitcnt lgkmcnt(0)
	v_mfma_f32_16x16x32_bf16 v[124:127], v[128:131], v[152:155], v[124:127]
	v_mfma_f32_16x16x32_bf16 v[120:123], v[136:139], v[152:155], v[120:123]
	v_mfma_f32_16x16x32_bf16 v[108:111], v[128:131], v[184:187], v[108:111]
	v_mfma_f32_16x16x32_bf16 v[104:107], v[136:139], v[184:187], v[104:107]
	v_mfma_f32_16x16x32_bf16 v[92:95], v[128:131], v[192:195], v[92:95]
	v_mfma_f32_16x16x32_bf16 v[88:91], v[136:139], v[192:195], v[88:91]
	v_mfma_f32_16x16x32_bf16 v[76:79], v[128:131], v[200:203], v[76:79]
	v_mfma_f32_16x16x32_bf16 v[72:75], v[136:139], v[200:203], v[72:75]
	v_mfma_f32_16x16x32_bf16 v[124:127], v[132:135], v[180:183], v[124:127]
	v_mfma_f32_16x16x32_bf16 v[120:123], v[140:143], v[180:183], v[120:123]
	v_mfma_f32_16x16x32_bf16 v[108:111], v[132:135], v[188:191], v[108:111]
	v_mfma_f32_16x16x32_bf16 v[104:107], v[140:143], v[188:191], v[104:107]
	v_mfma_f32_16x16x32_bf16 v[92:95], v[132:135], v[196:199], v[92:95]
	v_mfma_f32_16x16x32_bf16 v[88:91], v[140:143], v[196:199], v[88:91]
	v_mfma_f32_16x16x32_bf16 v[76:79], v[132:135], v[204:207], v[76:79]
	v_mfma_f32_16x16x32_bf16 v[72:75], v[140:143], v[204:207], v[72:75]
	s_setprio 0
	s_barrier
	s_add_i32 s10, 0, 0x1c000
	s_add_i32 s4, s43, s18
	v_add_u32_e32 v166, s10, v159
	v_lshl_add_u64 v[156:157], v[156:157], 0, s[76:77]
	s_mov_b32 m0, s4
	ds_read_b128 v[208:211], v166
	ds_read_b128 v[212:215], v166 offset:1024
	ds_read_b128 v[236:239], v166 offset:2048
	ds_read_b128 v[240:243], v166 offset:3072
	global_load_lds_dwordx4 v[156:157], off
	v_lshl_add_u64 v[156:157], v[172:173], 0, s[76:77]
	s_add_i32 m0, s4, 0x2000
	s_nop 0
	global_load_lds_dwordx4 v[156:157], off
	s_barrier
	s_waitcnt lgkmcnt(0)
	s_setprio 1
	s_waitcnt lgkmcnt(0)
	v_mfma_f32_16x16x32_bf16 v[116:119], v[208:211], v[152:155], v[116:119]
	v_mfma_f32_16x16x32_bf16 v[112:115], v[236:239], v[152:155], v[112:115]
	v_mfma_f32_16x16x32_bf16 v[100:103], v[208:211], v[184:187], v[100:103]
	v_mfma_f32_16x16x32_bf16 v[96:99], v[236:239], v[184:187], v[96:99]
	v_mfma_f32_16x16x32_bf16 v[84:87], v[208:211], v[192:195], v[84:87]
	v_mfma_f32_16x16x32_bf16 v[80:83], v[236:239], v[192:195], v[80:83]
	v_mfma_f32_16x16x32_bf16 v[68:71], v[208:211], v[200:203], v[68:71]
	v_mfma_f32_16x16x32_bf16 v[64:67], v[236:239], v[200:203], v[64:67]
	v_mfma_f32_16x16x32_bf16 v[116:119], v[212:215], v[180:183], v[116:119]
	v_mfma_f32_16x16x32_bf16 v[112:115], v[240:243], v[180:183], v[112:115]
	v_mfma_f32_16x16x32_bf16 v[100:103], v[212:215], v[188:191], v[100:103]
	v_mfma_f32_16x16x32_bf16 v[96:99], v[240:243], v[188:191], v[96:99]
	v_mfma_f32_16x16x32_bf16 v[84:87], v[212:215], v[196:199], v[84:87]
	v_mfma_f32_16x16x32_bf16 v[80:83], v[240:243], v[196:199], v[80:83]
	v_mfma_f32_16x16x32_bf16 v[68:71], v[212:215], v[204:207], v[68:71]
	v_mfma_f32_16x16x32_bf16 v[64:67], v[240:243], v[204:207], v[64:67]
	s_setprio 0
	s_mov_b32 m0, s23
	v_lshl_add_u64 v[156:157], v[174:175], 0, s[76:77]
	s_barrier
	ds_read_b128 v[152:155], v171 offset:49152
	ds_read_b128 v[180:183], v171 offset:50176
	ds_read_b128 v[184:187], v171 offset:51200
	ds_read_b128 v[188:191], v171 offset:52224
	ds_read_b128 v[192:195], v171 offset:53248
	ds_read_b128 v[196:199], v171 offset:54272
	ds_read_b128 v[200:203], v171 offset:55296
	ds_read_b128 v[204:207], v171 offset:56320
	global_load_lds_dwordx4 v[156:157], off
	v_lshl_add_u64 v[156:157], v[244:245], 0, s[76:77]
	s_mov_b32 m0, s24
	s_nop 0
	global_load_lds_dwordx4 v[156:157], off
	s_barrier
; #define PG8_WAIT_V(n) asm volatile("s_waitcnt vmcnt(" #n ")" ::: "memory")
; template <class Epi>
; __device__ __forceinline__ void gemm_phase(PG8_LAS unsigned char* lds, const Gemm g, const Sched& S, const Epi& E) {
;     ...
;             PG8_BAR; PG8_WAIT_L(0); PG8_MMA(1, 0, At, B0); PG8_BAR; PG8_SCHED;
;             PG8_STAGE(PG8_SB(1, 1), b3 + hsB, voffB);
;             PG8_WAIT_V(6); PG8_BAR; PG8_MMA(1, 1, At, B1); PG8_BAR;
;         }
;         E(acc, cur, wr, wc, fr, fq);
;   __device__ __forceinline__ void operator()(const f32x4 (&acc)[2][2][4][2], const pg8::Unit& u, int wr, int wc, int fr, int fq) const {
;     ...
;     if (kind == EPI_RESID) {
;       const float* md0 = modp + ((size_t)layer * 3 + condof(u.pm * 256)) * NMOD + slot * D;
; #pragma unroll
;       for (int bj = 0; bj < 2; ++bj)
; #pragma unroll
;         for (int n = 0; n < 2; ++n) {
;           float4 t = *(const float4*)(md0 + u.pn * 256 + bj * 128 + wc * 32 + n * 16 + fq * 4);
;           gsv[bj][n] = make_float4(t.x * scale, t.y * scale, t.z * scale, t.w * scale);
;         }
;     }
; #pragma unroll
;     for (int ai = 0; ai < 2; ++ai)
; #pragma unroll
;       for (int m = 0; m < 4; ++m) {
;         const int row = u.pm * 256 + ai * 128 + wr * 64 + m * 16 + fr;
;         if (kind == EPI_SWIGLU) {
; #pragma unroll
;           for (int bj = 0; bj < 2; ++bj) {
;             int hc = u.pn * 128 + bj * 64 + wc * 16 + fq * 4;
;             f32x4 g = acc[ai][bj][m][0], up = acc[ai][bj][m][1];
;             uint2 o; o.x = pack2(siluf_(g[0]) * up[0], siluf_(g[1]) * up[1]); o.y = pack2(siluf_(g[2]) * up[2], siluf_(g[3]) * up[3]);
;             *(uint2*)(outb + (size_t)row * ldo + hc) = o;
;           }
;         } else if (kind == EPI_RESID) {
;           float* xb;
;           { int b_ = row >= TPB ? 1 : 0; int u_ = row - b_ * TPB;
;             xb = (u_ < CTX) ? xctx + (size_t)(b_ * CTX + u_) * D : xout + ((size_t)b_ * SEQ + (u_ - CTX)) * D; }
;           const float* xr = (xb >= xout && xb < xout + (size_t)2 * SEQ * D) ? xin + (xb - xout) : xb;
; #pragma unroll
;           for (int bj = 0; bj < 2; ++bj)
; #pragma unroll
;             for (int n = 0; n < 2; ++n) {
;               int cc = u.pn * 256 + bj * 128 + wc * 32 + n * 16 + fq * 4;
;               const float4 gs = gsv[bj][n];
;               float4 xv = *(const float4*)(xr + cc);
;               f32x4 a = acc[ai][bj][m][n];
	s_waitcnt lgkmcnt(0)
	s_setprio 1
	s_waitcnt lgkmcnt(0)
	v_mfma_f32_16x16x32_bf16 v[60:63], v[128:131], v[152:155], v[60:63]
	v_mfma_f32_16x16x32_bf16 v[56:59], v[136:139], v[152:155], v[56:59]
	v_mfma_f32_16x16x32_bf16 v[44:47], v[128:131], v[184:187], v[44:47]
	v_mfma_f32_16x16x32_bf16 v[40:43], v[136:139], v[184:187], v[40:43]
	v_mfma_f32_16x16x32_bf16 v[28:31], v[128:131], v[192:195], v[28:31]
	v_mfma_f32_16x16x32_bf16 v[24:27], v[136:139], v[192:195], v[24:27]
	v_mfma_f32_16x16x32_bf16 v[12:15], v[128:131], v[200:203], v[12:15]
	v_mfma_f32_16x16x32_bf16 v[8:11], v[136:139], v[200:203], v[8:11]
	v_mfma_f32_16x16x32_bf16 v[60:63], v[132:135], v[180:183], v[60:63]
	v_mfma_f32_16x16x32_bf16 v[56:59], v[140:143], v[180:183], v[56:59]
	v_mfma_f32_16x16x32_bf16 v[44:47], v[132:135], v[188:191], v[44:47]
	v_mfma_f32_16x16x32_bf16 v[40:43], v[140:143], v[188:191], v[40:43]
	v_mfma_f32_16x16x32_bf16 v[28:31], v[132:135], v[196:199], v[28:31]
	v_mfma_f32_16x16x32_bf16 v[24:27], v[140:143], v[196:199], v[24:27]
	v_mfma_f32_16x16x32_bf16 v[12:15], v[132:135], v[204:207], v[12:15]
	v_mfma_f32_16x16x32_bf16 v[8:11], v[140:143], v[204:207], v[8:11]
	s_setprio 0
	s_barrier
	s_add_u32 s4, s8, 0xb0080
	s_addc_u32 s5, s9, 0
	s_add_i32 s8, s10, s18
	v_lshl_add_u64 v[128:129], s[4:5], 0, v[144:145]
	s_mov_b32 m0, s8
	s_nop 0
	global_load_lds_dwordx4 v[128:129], off
	v_lshl_add_u64 v[128:129], s[4:5], 0, v[146:147]
	s_add_i32 m0, s8, 0x2000
	s_nop 0
	global_load_lds_dwordx4 v[128:129], off
	s_waitcnt vmcnt(6)
	s_barrier
	s_setprio 1
	v_mfma_f32_16x16x32_bf16 v[52:55], v[208:211], v[152:155], v[52:55]
	v_mfma_f32_16x16x32_bf16 v[48:51], v[236:239], v[152:155], v[48:51]
	v_mfma_f32_16x16x32_bf16 v[36:39], v[208:211], v[184:187], v[36:39]
	v_mfma_f32_16x16x32_bf16 v[32:35], v[236:239], v[184:187], v[32:35]
	v_mfma_f32_16x16x32_bf16 v[20:23], v[208:211], v[192:195], v[20:23]
	v_mfma_f32_16x16x32_bf16 v[16:19], v[236:239], v[192:195], v[16:19]
	v_mfma_f32_16x16x32_bf16 v[4:7], v[208:211], v[200:203], v[4:7]
	v_mfma_f32_16x16x32_bf16 v[0:3], v[236:239], v[200:203], v[0:3]
	v_mfma_f32_16x16x32_bf16 v[52:55], v[212:215], v[180:183], v[52:55]
	v_mfma_f32_16x16x32_bf16 v[48:51], v[240:243], v[180:183], v[48:51]
	v_mfma_f32_16x16x32_bf16 v[36:39], v[212:215], v[188:191], v[36:39]
	v_mfma_f32_16x16x32_bf16 v[32:35], v[240:243], v[188:191], v[32:35]
	v_mfma_f32_16x16x32_bf16 v[20:23], v[212:215], v[196:199], v[20:23]
	v_mfma_f32_16x16x32_bf16 v[16:19], v[240:243], v[196:199], v[16:19]
	v_mfma_f32_16x16x32_bf16 v[4:7], v[212:215], v[204:207], v[4:7]
	v_mfma_f32_16x16x32_bf16 v[0:3], v[240:243], v[204:207], v[0:3]
	s_setprio 0
	s_add_i32 s42, s42, 2
	s_add_u32 s2, s2, 0x100
	s_addc_u32 s3, s3, 0
	s_cmp_gt_u32 s42, 41
	s_mov_b64 s[4:5], s[6:7]
	s_barrier
	s_cbranch_scc0 .LBB0_845
	s_lshl_b32 s8, s39, 8
	s_cmp_gt_i32 s39, 32
	s_cselect_b64 s[2:3], -1, 0
	v_cndmask_b32_e64 v128, 0, 1, s[2:3]
	s_and_b64 s[2:3], s[2:3], exec
	s_cselect_b32 s2, 0xffffdf00, 0
	s_add_i32 s2, s2, s8
	s_cmpk_gt_i32 s2, 0xff
	v_readfirstlane_b32 s2, v128
	s_cselect_b32 s2, s2, 2
	s_mul_i32 s3, s17, 3
	s_add_i32 s2, s2, s3
	s_mul_i32 s2, s2, 0x9000
	s_add_u32 s6, s27, s2
	s_addc_u32 s7, s29, 0
	s_lshl_b32 s4, s38, 8
	s_ashr_i32 s5, s4, 31
	s_lshl_b64 s[2:3], s[4:5], 2
	s_add_u32 s2, s6, s2
	s_addc_u32 s3, s7, s3
	s_add_u32 s2, s2, s30
	s_addc_u32 s3, s3, 0
	global_load_dwordx4 v[140:143], v178, s[2:3]
	global_load_dwordx4 v[136:139], v178, s[2:3] offset:64
	global_load_dwordx4 v[132:135], v178, s[2:3] offset:512
	global_load_dwordx4 v[128:131], v178, s[2:3] offset:576
	v_add_u32_e32 v179, s8, v158
	s_movk_i32 s2, 0x20ff
	v_cmp_lt_i32_e32 vcc, s2, v179
	s_nop 1
	v_cndmask_b32_e32 v152, 0, v228, vcc
	v_add_u32_e32 v152, v152, v179
	v_cmp_lt_i32_e64 s[42:43], s81, v152
	s_and_saveexec_b64 s[2:3], s[42:43]
	s_xor_b64 s[2:3], exec, s[2:3]
	v_cndmask_b32_e32 v153, 0, v230, vcc
	s_movk_i32 s5, 0xff00
	v_add3_u32 v166, v152, v153, s5
	v_mov_b64_e32 v[154:155], v[166:167]
	s_or_saveexec_b64 s[6:7], s[2:3]
	v_mov_b64_e32 v[156:157], s[48:49]
	s_xor_b64 exec, exec, s[6:7]
	v_cndmask_b32_e32 v153, 0, v229, vcc
	v_add_u32_e32 v154, v152, v153
	v_ashrrev_i32_e32 v155, 31, v154
	v_mov_b64_e32 v[156:157], s[46:47]
	s_or_b64 exec, exec, s[6:7]
	s_waitcnt vmcnt(0)
	v_pk_mul_f32 v[152:153], v[140:141], 0.5 op_sel_hi:[1,0]
	v_pk_mul_f32 v[140:141], v[136:137], 0.5 op_sel_hi:[1,0]
	v_pk_mul_f32 v[136:137], v[132:133], 0.5 op_sel_hi:[1,0]
	v_pk_mul_f32 v[132:133], v[134:135], 0.5 op_sel_hi:[1,0]
	v_lshlrev_b64 v[134:135], 12, v[154:155]
	v_lshl_add_u64 v[154:155], v[156:157], 0, v[134:135]
	v_cmp_le_u64_e32 vcc, s[48:49], v[154:155]
	v_cmp_gt_u64_e64 s[42:43], s[58:59], v[154:155]
	s_and_b64 vcc, vcc, s[42:43]
	v_subrev_co_u32_e64 v134, s[42:43], s48, v154
	v_mov_b32_e32 v135, s49
	s_nop 0
	v_subb_co_u32_e64 v135, s[42:43], v155, v135, s[42:43]
	v_lshl_add_u64 v[134:135], s[56:57], 0, v[134:135]
	v_cndmask_b32_e32 v156, v154, v134, vcc
	v_or_b32_e32 v134, s4, v160
	v_cndmask_b32_e32 v157, v155, v135, vcc
	v_ashrrev_i32_e32 v135, 31, v134
	v_lshlrev_b64 v[134:135], 2, v[134:135]
	v_lshl_add_u64 v[172:173], v[156:157], 0, v[134:135]
	v_lshl_add_u64 v[174:175], v[154:155], 0, v[134:135]
	global_load_dwordx4 v[180:183], v[172:173], off
	global_load_dwordx4 v[184:187], v[172:173], off offset:64
	global_load_dwordx4 v[188:191], v[172:173], off offset:512
	global_load_dwordx4 v[192:195], v[172:173], off offset:576
	v_pk_mul_f32 v[142:143], v[142:143], 0.5 op_sel_hi:[1,0]
	v_pk_mul_f32 v[138:139], v[138:139], 0.5 op_sel_hi:[1,0]
	v_pk_mul_f32 v[128:129], v[128:129], 0.5 op_sel_hi:[1,0]
	v_pk_mul_f32 v[130:131], v[130:131], 0.5 op_sel_hi:[1,0]
	s_movk_i32 s2, 0x20ff
	v_add_co_u32_e32 v212, vcc, 0x10000, v172
	s_nop 1
	v_addc_co_u32_e32 v213, vcc, 0, v173, vcc
	global_load_dwordx4 v[196:199], v[212:213], off
	global_load_dwordx4 v[200:203], v[212:213], off offset:64
	global_load_dwordx4 v[204:207], v[212:213], off offset:512
	global_load_dwordx4 v[208:211], v[212:213], off offset:576
	s_waitcnt vmcnt(7)
;   __device__ __forceinline__ void operator()(const f32x4 (&acc)[2][2][4][2], const pg8::Unit& u, int wr, int wc, int fr, int fq) const {
;     ...
;         } else if (kind == EPI_RESID) {
;           float* xb;
;           { int b_ = row >= TPB ? 1 : 0; int u_ = row - b_ * TPB;
;             xb = (u_ < CTX) ? xctx + (size_t)(b_ * CTX + u_) * D : xout + ((size_t)b_ * SEQ + (u_ - CTX)) * D; }
;           const float* xr = (xb >= xout && xb < xout + (size_t)2 * SEQ * D) ? xin + (xb - xout) : xb;
; #pragma unroll
;           for (int bj = 0; bj < 2; ++bj)
; #pragma unroll
;             for (int n = 0; n < 2; ++n) {
;               int cc = u.pn * 256 + bj * 128 + wc * 32 + n * 16 + fq * 4;
;               const float4 gs = gsv[bj][n];
;               float4 xv = *(const float4*)(xr + cc);
;               f32x4 a = acc[ai][bj][m][n];
;               xv.x += gs.x * a[0]; xv.y += gs.y * a[1]; xv.z += gs.z * a[2]; xv.w += gs.w * a[3];
;               *(float4*)(xb + cc) = xv;
;             }
	v_pk_fma_f32 v[124:125], v[124:125], v[152:153], v[180:181]
	v_pk_fma_f32 v[126:127], v[126:127], v[142:143], v[182:183]
	global_store_dwordx4 v[174:175], v[124:127], off
	s_waitcnt vmcnt(7)
	v_pk_fma_f32 v[120:121], v[120:121], v[140:141], v[184:185]
	v_pk_fma_f32 v[122:123], v[122:123], v[138:139], v[186:187]
	global_store_dwordx4 v[174:175], v[120:123], off offset:64
	s_waitcnt vmcnt(7)
	v_pk_fma_f32 v[116:117], v[116:117], v[136:137], v[188:189]
	v_pk_fma_f32 v[118:119], v[118:119], v[132:133], v[190:191]
	global_store_dwordx4 v[174:175], v[116:119], off offset:512
	s_waitcnt vmcnt(7)
	v_pk_fma_f32 v[112:113], v[112:113], v[128:129], v[192:193]
	v_pk_fma_f32 v[114:115], v[114:115], v[130:131], v[194:195]
	global_store_dwordx4 v[174:175], v[112:115], off offset:576
	v_add_co_u32_e32 v212, vcc, 0x20000, v172
	s_nop 1
	v_addc_co_u32_e32 v213, vcc, 0, v173, vcc
	global_load_dwordx4 v[180:183], v[212:213], off
	global_load_dwordx4 v[184:187], v[212:213], off offset:64
	global_load_dwordx4 v[188:191], v[212:213], off offset:512
	global_load_dwordx4 v[192:195], v[212:213], off offset:576
	v_add_co_u32_e32 v236, vcc, 0x10000, v174
	s_nop 1
	v_addc_co_u32_e32 v237, vcc, 0, v175, vcc
	s_waitcnt vmcnt(11)
	v_pk_fma_f32 v[108:109], v[108:109], v[152:153], v[196:197]
	v_pk_fma_f32 v[110:111], v[110:111], v[142:143], v[198:199]
	global_store_dwordx4 v[236:237], v[108:111], off
	s_waitcnt vmcnt(11)
	v_pk_fma_f32 v[104:105], v[104:105], v[140:141], v[200:201]
	v_pk_fma_f32 v[106:107], v[106:107], v[138:139], v[202:203]
	global_store_dwordx4 v[236:237], v[104:107], off offset:64
	s_waitcnt vmcnt(11)
	v_pk_fma_f32 v[100:101], v[100:101], v[136:137], v[204:205]
	v_pk_fma_f32 v[102:103], v[102:103], v[132:133], v[206:207]
	global_store_dwordx4 v[236:237], v[100:103], off offset:512
	s_waitcnt vmcnt(11)
	v_pk_fma_f32 v[96:97], v[96:97], v[128:129], v[208:209]
	v_pk_fma_f32 v[98:99], v[98:99], v[130:131], v[210:211]
	global_store_dwordx4 v[236:237], v[96:99], off offset:576
	v_add_co_u32_e32 v212, vcc, 0x30000, v172
	s_nop 1
	v_addc_co_u32_e32 v213, vcc, 0, v173, vcc
	global_load_dwordx4 v[196:199], v[212:213], off
	global_load_dwordx4 v[200:203], v[212:213], off offset:64
	global_load_dwordx4 v[204:207], v[212:213], off offset:512
	global_load_dwordx4 v[208:211], v[212:213], off offset:576
	v_add_co_u32_e32 v236, vcc, 0x20000, v174
	s_nop 1
	v_addc_co_u32_e32 v237, vcc, 0, v175, vcc
	s_waitcnt vmcnt(11)
	v_pk_fma_f32 v[92:93], v[92:93], v[152:153], v[180:181]
	v_pk_fma_f32 v[94:95], v[94:95], v[142:143], v[182:183]
	global_store_dwordx4 v[236:237], v[92:95], off
	s_waitcnt vmcnt(11)
	v_pk_fma_f32 v[88:89], v[88:89], v[140:141], v[184:185]
	v_pk_fma_f32 v[90:91], v[90:91], v[138:139], v[186:187]
	global_store_dwordx4 v[236:237], v[88:91], off offset:64
	s_waitcnt vmcnt(11)
	v_pk_fma_f32 v[84:85], v[84:85], v[136:137], v[188:189]
	v_pk_fma_f32 v[86:87], v[86:87], v[132:133], v[190:191]
	global_store_dwordx4 v[236:237], v[84:87], off offset:512
	s_waitcnt vmcnt(11)
	v_pk_fma_f32 v[80:81], v[80:81], v[128:129], v[192:193]
	v_pk_fma_f32 v[82:83], v[82:83], v[130:131], v[194:195]
	global_store_dwordx4 v[236:237], v[80:83], off offset:576
	v_add_co_u32_e32 v212, vcc, 0x80000, v172
	s_nop 1
	v_addc_co_u32_e32 v213, vcc, 0, v173, vcc
	global_load_dwordx4 v[180:183], v[212:213], off
	global_load_dwordx4 v[184:187], v[212:213], off offset:64
	global_load_dwordx4 v[188:191], v[212:213], off offset:512
	global_load_dwordx4 v[192:195], v[212:213], off offset:576
	v_add_co_u32_e32 v236, vcc, 0x30000, v174
	s_nop 1
	v_addc_co_u32_e32 v237, vcc, 0, v175, vcc
	s_waitcnt vmcnt(11)
	v_pk_fma_f32 v[76:77], v[76:77], v[152:153], v[196:197]
	v_pk_fma_f32 v[78:79], v[78:79], v[142:143], v[198:199]
	global_store_dwordx4 v[236:237], v[76:79], off
	s_waitcnt vmcnt(11)
	v_pk_fma_f32 v[72:73], v[72:73], v[140:141], v[200:201]
	v_pk_fma_f32 v[74:75], v[74:75], v[138:139], v[202:203]
	global_store_dwordx4 v[236:237], v[72:75], off offset:64
	s_waitcnt vmcnt(11)
	v_pk_fma_f32 v[68:69], v[68:69], v[136:137], v[204:205]
	v_pk_fma_f32 v[70:71], v[70:71], v[132:133], v[206:207]
	global_store_dwordx4 v[236:237], v[68:71], off offset:512
	s_waitcnt vmcnt(11)
	v_pk_fma_f32 v[64:65], v[64:65], v[128:129], v[208:209]
	v_pk_fma_f32 v[66:67], v[66:67], v[130:131], v[210:211]
	global_store_dwordx4 v[236:237], v[64:67], off offset:576
	v_add_co_u32_e32 v212, vcc, 0x90000, v172
	s_nop 1
	v_addc_co_u32_e32 v213, vcc, 0, v173, vcc
	global_load_dwordx4 v[196:199], v[212:213], off
	global_load_dwordx4 v[200:203], v[212:213], off offset:64
	global_load_dwordx4 v[204:207], v[212:213], off offset:512
	global_load_dwordx4 v[208:211], v[212:213], off offset:576
	v_add_co_u32_e32 v236, vcc, 0x80000, v174
	s_nop 1
	v_addc_co_u32_e32 v237, vcc, 0, v175, vcc
	s_waitcnt vmcnt(11)
	v_pk_fma_f32 v[60:61], v[60:61], v[152:153], v[180:181]
	v_pk_fma_f32 v[62:63], v[62:63], v[142:143], v[182:183]
	global_store_dwordx4 v[236:237], v[60:63], off
	s_waitcnt vmcnt(11)
	v_pk_fma_f32 v[56:57], v[56:57], v[140:141], v[184:185]
	v_pk_fma_f32 v[58:59], v[58:59], v[138:139], v[186:187]
	global_store_dwordx4 v[236:237], v[56:59], off offset:64
	s_waitcnt vmcnt(11)
	v_pk_fma_f32 v[52:53], v[52:53], v[136:137], v[188:189]
	v_pk_fma_f32 v[54:55], v[54:55], v[132:133], v[190:191]
	global_store_dwordx4 v[236:237], v[52:55], off offset:512
	s_waitcnt vmcnt(11)
;   __device__ __forceinline__ void operator()(const f32x4 (&acc)[2][2][4][2], const pg8::Unit& u, int wr, int wc, int fr, int fq) const {
;     ...
;         } else if (kind == EPI_RESID) {
;           float* xb;
;           { int b_ = row >= TPB ? 1 : 0; int u_ = row - b_ * TPB;
;             xb = (u_ < CTX) ? xctx + (size_t)(b_ * CTX + u_) * D : xout + ((size_t)b_ * SEQ + (u_ - CTX)) * D; }
;           const float* xr = (xb >= xout && xb < xout + (size_t)2 * SEQ * D) ? xin + (xb - xout) : xb;
; #pragma unroll
;           for (int bj = 0; bj < 2; ++bj)
; #pragma unroll
;             for (int n = 0; n < 2; ++n) {
;               int cc = u.pn * 256 + bj * 128 + wc * 32 + n * 16 + fq * 4;
;               const float4 gs = gsv[bj][n];
;               float4 xv = *(const float4*)(xr + cc);
;               f32x4 a = acc[ai][bj][m][n];
;               xv.x += gs.x * a[0]; xv.y += gs.y * a[1]; xv.z += gs.z * a[2]; xv.w += gs.w * a[3];
;               *(float4*)(xb + cc) = xv;
;             }
	v_pk_fma_f32 v[48:49], v[48:49], v[128:129], v[192:193]
	v_pk_fma_f32 v[50:51], v[50:51], v[130:131], v[194:195]
	global_store_dwordx4 v[236:237], v[48:51], off offset:576
	v_add_co_u32_e32 v212, vcc, 0xa0000, v172
	s_nop 1
	v_addc_co_u32_e32 v213, vcc, 0, v173, vcc
	global_load_dwordx4 v[180:183], v[212:213], off
	global_load_dwordx4 v[184:187], v[212:213], off offset:64
	global_load_dwordx4 v[188:191], v[212:213], off offset:512
	global_load_dwordx4 v[192:195], v[212:213], off offset:576
	v_add_co_u32_e32 v236, vcc, 0x90000, v174
	s_nop 1
	v_addc_co_u32_e32 v237, vcc, 0, v175, vcc
	s_waitcnt vmcnt(11)
	v_pk_fma_f32 v[44:45], v[44:45], v[152:153], v[196:197]
	v_pk_fma_f32 v[46:47], v[46:47], v[142:143], v[198:199]
	global_store_dwordx4 v[236:237], v[44:47], off
	s_waitcnt vmcnt(11)
	v_pk_fma_f32 v[40:41], v[40:41], v[140:141], v[200:201]
	v_pk_fma_f32 v[42:43], v[42:43], v[138:139], v[202:203]
	global_store_dwordx4 v[236:237], v[40:43], off offset:64
	s_waitcnt vmcnt(11)
	v_pk_fma_f32 v[36:37], v[36:37], v[136:137], v[204:205]
	v_pk_fma_f32 v[38:39], v[38:39], v[132:133], v[206:207]
	global_store_dwordx4 v[236:237], v[36:39], off offset:512
	s_waitcnt vmcnt(11)
	v_pk_fma_f32 v[32:33], v[32:33], v[128:129], v[208:209]
	v_pk_fma_f32 v[34:35], v[34:35], v[130:131], v[210:211]
	global_store_dwordx4 v[236:237], v[32:35], off offset:576
	v_add_co_u32_e32 v212, vcc, 0xb0000, v172
	s_nop 1
	v_addc_co_u32_e32 v213, vcc, 0, v173, vcc
	global_load_dwordx4 v[196:199], v[212:213], off
	global_load_dwordx4 v[200:203], v[212:213], off offset:64
	global_load_dwordx4 v[204:207], v[212:213], off offset:512
	global_load_dwordx4 v[208:211], v[212:213], off offset:576
	v_add_co_u32_e32 v236, vcc, 0xa0000, v174
	s_nop 1
	v_addc_co_u32_e32 v237, vcc, 0, v175, vcc
	s_waitcnt vmcnt(11)
	v_pk_fma_f32 v[28:29], v[28:29], v[152:153], v[180:181]
	v_pk_fma_f32 v[30:31], v[30:31], v[142:143], v[182:183]
	global_store_dwordx4 v[236:237], v[28:31], off
	s_waitcnt vmcnt(11)
	v_pk_fma_f32 v[24:25], v[24:25], v[140:141], v[184:185]
	v_pk_fma_f32 v[26:27], v[26:27], v[138:139], v[186:187]
	global_store_dwordx4 v[236:237], v[24:27], off offset:64
	s_waitcnt vmcnt(11)
	v_pk_fma_f32 v[20:21], v[20:21], v[136:137], v[188:189]
	v_pk_fma_f32 v[22:23], v[22:23], v[132:133], v[190:191]
	global_store_dwordx4 v[236:237], v[20:23], off offset:512
	s_waitcnt vmcnt(11)
	v_pk_fma_f32 v[16:17], v[16:17], v[128:129], v[192:193]
	v_pk_fma_f32 v[18:19], v[18:19], v[130:131], v[194:195]
	global_store_dwordx4 v[236:237], v[16:19], off offset:576
	v_add_co_u32_e32 v236, vcc, 0xb0000, v174
	s_nop 1
	v_addc_co_u32_e32 v237, vcc, 0, v175, vcc
	s_waitcnt vmcnt(7)
	v_pk_fma_f32 v[12:13], v[12:13], v[152:153], v[196:197]
	v_pk_fma_f32 v[14:15], v[14:15], v[142:143], v[198:199]
	global_store_dwordx4 v[236:237], v[12:15], off
	s_waitcnt vmcnt(7)
	v_pk_fma_f32 v[8:9], v[8:9], v[140:141], v[200:201]
	v_pk_fma_f32 v[10:11], v[10:11], v[138:139], v[202:203]
	global_store_dwordx4 v[236:237], v[8:11], off offset:64
	s_waitcnt vmcnt(7)
	v_pk_fma_f32 v[4:5], v[4:5], v[136:137], v[204:205]
	v_pk_fma_f32 v[6:7], v[6:7], v[132:133], v[206:207]
	global_store_dwordx4 v[236:237], v[4:7], off offset:512
	s_waitcnt vmcnt(7)
	v_pk_fma_f32 v[0:1], v[0:1], v[128:129], v[208:209]
	v_pk_fma_f32 v[2:3], v[2:3], v[130:131], v[210:211]
	global_store_dwordx4 v[236:237], v[0:3], off offset:576
	s_nop 1
	v_add_u32_e32 v112, s8, v161
	v_cmp_lt_i32_e32 vcc, s2, v112
	s_nop 1
	v_cndmask_b32_e32 v113, 0, v228, vcc
	v_add_u32_e32 v116, v113, v112
	v_cmp_lt_i32_e64 s[42:43], s81, v116
	s_and_saveexec_b64 s[2:3], s[42:43]
	s_xor_b64 s[2:3], exec, s[2:3]
	v_cndmask_b32_e32 v112, 0, v230, vcc
	s_movk_i32 s4, 0xff00
	v_add3_u32 v166, v116, v112, s4
	v_mov_b64_e32 v[112:113], v[166:167]
	s_or_saveexec_b64 s[4:5], s[2:3]
	v_mov_b64_e32 v[114:115], s[48:49]
	s_xor_b64 exec, exec, s[4:5]
	v_cndmask_b32_e32 v112, 0, v229, vcc
	v_add_u32_e32 v112, v116, v112
	v_ashrrev_i32_e32 v113, 31, v112
	v_mov_b64_e32 v[114:115], s[46:47]
	s_or_b64 exec, exec, s[4:5]
	v_lshlrev_b64 v[112:113], 12, v[112:113]
	v_lshl_add_u64 v[112:113], v[114:115], 0, v[112:113]
	v_cmp_le_u64_e32 vcc, s[48:49], v[112:113]
	v_cmp_gt_u64_e64 s[42:43], s[58:59], v[112:113]
	s_and_b64 vcc, vcc, s[42:43]
	v_subrev_co_u32_e64 v114, s[42:43], s48, v112
	v_mov_b32_e32 v115, s49
	s_nop 0
	v_subb_co_u32_e64 v115, s[42:43], v113, v115, s[42:43]
	v_lshl_add_u64 v[114:115], s[56:57], 0, v[114:115]
	v_cndmask_b32_e32 v115, v113, v115, vcc
	v_cndmask_b32_e32 v114, v112, v114, vcc
	v_lshl_add_u64 v[116:117], v[114:115], 0, v[134:135]
	v_lshl_add_u64 v[118:119], v[112:113], 0, v[134:135]
	s_movk_i32 s2, 0x20ff
	s_nop 1
	v_add_u32_e32 v96, s8, v162
	v_cmp_lt_i32_e32 vcc, s2, v96
	s_nop 1
	v_cndmask_b32_e32 v97, 0, v228, vcc
	v_add_u32_e32 v100, v97, v96
	v_cmp_lt_i32_e64 s[42:43], s81, v100
	s_and_saveexec_b64 s[2:3], s[42:43]
	s_xor_b64 s[2:3], exec, s[2:3]
	v_cndmask_b32_e32 v96, 0, v230, vcc
	s_movk_i32 s4, 0xff00
	v_add3_u32 v166, v100, v96, s4
	v_mov_b64_e32 v[96:97], v[166:167]
	s_or_saveexec_b64 s[4:5], s[2:3]
	v_mov_b64_e32 v[98:99], s[48:49]
	s_xor_b64 exec, exec, s[4:5]
	v_cndmask_b32_e32 v96, 0, v229, vcc
	v_add_u32_e32 v96, v100, v96
	v_ashrrev_i32_e32 v97, 31, v96
	v_mov_b64_e32 v[98:99], s[46:47]
	s_or_b64 exec, exec, s[4:5]
	v_lshlrev_b64 v[96:97], 12, v[96:97]
	v_lshl_add_u64 v[96:97], v[98:99], 0, v[96:97]
	v_cmp_le_u64_e32 vcc, s[48:49], v[96:97]
	v_cmp_gt_u64_e64 s[42:43], s[58:59], v[96:97]
	s_and_b64 vcc, vcc, s[42:43]
	v_subrev_co_u32_e64 v98, s[42:43], s48, v96
	v_mov_b32_e32 v99, s49
	s_nop 0
	v_subb_co_u32_e64 v99, s[42:43], v97, v99, s[42:43]
;   __device__ __forceinline__ void operator()(const f32x4 (&acc)[2][2][4][2], const pg8::Unit& u, int wr, int wc, int fr, int fq) const {
;     ...
;           float* xb;
;           { int b_ = row >= TPB ? 1 : 0; int u_ = row - b_ * TPB;
;             xb = (u_ < CTX) ? xctx + (size_t)(b_ * CTX + u_) * D : xout + ((size_t)b_ * SEQ + (u_ - CTX)) * D; }
;           const float* xr = (xb >= xout && xb < xout + (size_t)2 * SEQ * D) ? xin + (xb - xout) : xb;
; #pragma unroll
;           for (int bj = 0; bj < 2; ++bj)
; #pragma unroll
;             for (int n = 0; n < 2; ++n) {
;               int cc = u.pn * 256 + bj * 128 + wc * 32 + n * 16 + fq * 4;
;               const float4 gs = gsv[bj][n];
;               float4 xv = *(const float4*)(xr + cc);
;               f32x4 a = acc[ai][bj][m][n];
;               xv.x += gs.x * a[0]; xv.y += gs.y * a[1]; xv.z += gs.z * a[2]; xv.w += gs.w * a[3];
;               *(float4*)(xb + cc) = xv;
;             }
	v_lshl_add_u64 v[98:99], s[56:57], 0, v[98:99]
	v_cndmask_b32_e32 v99, v97, v99, vcc
	v_cndmask_b32_e32 v98, v96, v98, vcc
	v_lshl_add_u64 v[100:101], v[98:99], 0, v[134:135]
	v_lshl_add_u64 v[102:103], v[96:97], 0, v[134:135]
	s_movk_i32 s2, 0x20ff
	s_nop 1
	v_add_u32_e32 v80, s8, v163
	v_cmp_lt_i32_e32 vcc, s2, v80
	s_nop 1
	v_cndmask_b32_e32 v81, 0, v228, vcc
	v_add_u32_e32 v84, v81, v80
	v_cmp_lt_i32_e64 s[42:43], s81, v84
	s_and_saveexec_b64 s[2:3], s[42:43]
	s_xor_b64 s[2:3], exec, s[2:3]
	v_cndmask_b32_e32 v80, 0, v230, vcc
	s_movk_i32 s4, 0xff00
	v_add3_u32 v166, v84, v80, s4
	v_mov_b64_e32 v[80:81], v[166:167]
	s_or_saveexec_b64 s[4:5], s[2:3]
	v_mov_b64_e32 v[82:83], s[48:49]
	s_xor_b64 exec, exec, s[4:5]
	v_cndmask_b32_e32 v80, 0, v229, vcc
	v_add_u32_e32 v80, v84, v80
	v_ashrrev_i32_e32 v81, 31, v80
	v_mov_b64_e32 v[82:83], s[46:47]
	s_or_b64 exec, exec, s[4:5]
	v_lshlrev_b64 v[80:81], 12, v[80:81]
	v_lshl_add_u64 v[80:81], v[82:83], 0, v[80:81]
	v_cmp_le_u64_e32 vcc, s[48:49], v[80:81]
	v_cmp_gt_u64_e64 s[42:43], s[58:59], v[80:81]
	s_and_b64 vcc, vcc, s[42:43]
	v_subrev_co_u32_e64 v82, s[42:43], s48, v80
	v_mov_b32_e32 v83, s49
	s_nop 0
	v_subb_co_u32_e64 v83, s[42:43], v81, v83, s[42:43]
	v_lshl_add_u64 v[82:83], s[56:57], 0, v[82:83]
	v_cndmask_b32_e32 v83, v81, v83, vcc
	v_cndmask_b32_e32 v82, v80, v82, vcc
	v_lshl_add_u64 v[84:85], v[82:83], 0, v[134:135]
	v_lshl_add_u64 v[86:87], v[80:81], 0, v[134:135]
	s_movk_i32 s2, 0x20ff
	s_nop 1
	v_add_u32_e32 v64, 0x80, v179
	v_cmp_lt_i32_e32 vcc, s2, v64
	s_nop 1
	v_cndmask_b32_e32 v65, 0, v228, vcc
	v_add_u32_e32 v68, v65, v64
	v_cmp_lt_i32_e64 s[42:43], s81, v68
	s_and_saveexec_b64 s[2:3], s[42:43]
	s_xor_b64 s[2:3], exec, s[2:3]
	v_cndmask_b32_e32 v64, 0, v230, vcc
	s_movk_i32 s4, 0xff00
	v_add3_u32 v166, v68, v64, s4
	v_mov_b64_e32 v[64:65], v[166:167]
	s_or_saveexec_b64 s[4:5], s[2:3]
	v_mov_b64_e32 v[66:67], s[48:49]
	s_xor_b64 exec, exec, s[4:5]
	v_cndmask_b32_e32 v64, 0, v229, vcc
	v_add_u32_e32 v64, v68, v64
	v_ashrrev_i32_e32 v65, 31, v64
	v_mov_b64_e32 v[66:67], s[46:47]
	s_or_b64 exec, exec, s[4:5]
	v_lshlrev_b64 v[64:65], 12, v[64:65]
	v_lshl_add_u64 v[64:65], v[66:67], 0, v[64:65]
	v_cmp_le_u64_e32 vcc, s[48:49], v[64:65]
	v_cmp_gt_u64_e64 s[42:43], s[58:59], v[64:65]
	s_and_b64 vcc, vcc, s[42:43]
	v_subrev_co_u32_e64 v66, s[42:43], s48, v64
	v_mov_b32_e32 v67, s49
	s_nop 0
	v_subb_co_u32_e64 v67, s[42:43], v65, v67, s[42:43]
	v_lshl_add_u64 v[66:67], s[56:57], 0, v[66:67]
	v_cndmask_b32_e32 v67, v65, v67, vcc
	v_cndmask_b32_e32 v66, v64, v66, vcc
	v_lshl_add_u64 v[68:69], v[66:67], 0, v[134:135]
	v_lshl_add_u64 v[70:71], v[64:65], 0, v[134:135]
	s_movk_i32 s2, 0x20ff
	s_nop 1
	v_add_u32_e32 v48, 0x90, v179
	v_cmp_lt_i32_e32 vcc, s2, v48
	s_nop 1
	v_cndmask_b32_e32 v49, 0, v228, vcc
	v_add_u32_e32 v52, v49, v48
	v_cmp_lt_i32_e64 s[42:43], s81, v52
	s_and_saveexec_b64 s[2:3], s[42:43]
	s_xor_b64 s[2:3], exec, s[2:3]
	v_cndmask_b32_e32 v48, 0, v230, vcc
	s_movk_i32 s4, 0xff00
	v_add3_u32 v166, v52, v48, s4
	v_mov_b64_e32 v[48:49], v[166:167]
	s_or_saveexec_b64 s[4:5], s[2:3]
	v_mov_b64_e32 v[50:51], s[48:49]
	s_xor_b64 exec, exec, s[4:5]
	v_cndmask_b32_e32 v48, 0, v229, vcc
	v_add_u32_e32 v48, v52, v48
	v_ashrrev_i32_e32 v49, 31, v48
	v_mov_b64_e32 v[50:51], s[46:47]
	s_or_b64 exec, exec, s[4:5]
	v_lshlrev_b64 v[48:49], 12, v[48:49]
	v_lshl_add_u64 v[48:49], v[50:51], 0, v[48:49]
	v_cmp_le_u64_e32 vcc, s[48:49], v[48:49]
	v_cmp_gt_u64_e64 s[42:43], s[58:59], v[48:49]
	s_and_b64 vcc, vcc, s[42:43]
	v_subrev_co_u32_e64 v50, s[42:43], s48, v48
	v_mov_b32_e32 v51, s49
	s_nop 0
	v_subb_co_u32_e64 v51, s[42:43], v49, v51, s[42:43]
	v_lshl_add_u64 v[50:51], s[56:57], 0, v[50:51]
	v_cndmask_b32_e32 v51, v49, v51, vcc
	v_cndmask_b32_e32 v50, v48, v50, vcc
	v_lshl_add_u64 v[52:53], v[50:51], 0, v[134:135]
	v_lshl_add_u64 v[54:55], v[48:49], 0, v[134:135]
	s_movk_i32 s2, 0x20ff
	s_nop 1
	v_add_u32_e32 v32, 0xa0, v179
	v_cmp_lt_i32_e32 vcc, s2, v32
	s_nop 1
	v_cndmask_b32_e32 v33, 0, v228, vcc
	v_add_u32_e32 v36, v33, v32
	v_cmp_lt_i32_e64 s[42:43], s81, v36
	s_and_saveexec_b64 s[2:3], s[42:43]
	s_xor_b64 s[2:3], exec, s[2:3]
	v_cndmask_b32_e32 v32, 0, v230, vcc
	s_movk_i32 s4, 0xff00
	v_add3_u32 v166, v36, v32, s4
	v_mov_b64_e32 v[32:33], v[166:167]
	s_or_saveexec_b64 s[4:5], s[2:3]
	v_mov_b64_e32 v[34:35], s[48:49]
	s_xor_b64 exec, exec, s[4:5]
	v_cndmask_b32_e32 v32, 0, v229, vcc
	v_add_u32_e32 v32, v36, v32
	v_ashrrev_i32_e32 v33, 31, v32
	v_mov_b64_e32 v[34:35], s[46:47]
	s_or_b64 exec, exec, s[4:5]
	v_lshlrev_b64 v[32:33], 12, v[32:33]
	v_lshl_add_u64 v[32:33], v[34:35], 0, v[32:33]
	v_cmp_le_u64_e32 vcc, s[48:49], v[32:33]
	v_cmp_gt_u64_e64 s[42:43], s[58:59], v[32:33]
	s_and_b64 vcc, vcc, s[42:43]
	v_subrev_co_u32_e64 v34, s[42:43], s48, v32
	v_mov_b32_e32 v35, s49
	s_nop 0
	v_subb_co_u32_e64 v35, s[42:43], v33, v35, s[42:43]
	v_lshl_add_u64 v[34:35], s[56:57], 0, v[34:35]
	v_cndmask_b32_e32 v35, v33, v35, vcc
	v_cndmask_b32_e32 v34, v32, v34, vcc
	v_lshl_add_u64 v[36:37], v[34:35], 0, v[134:135]
	v_lshl_add_u64 v[38:39], v[32:33], 0, v[134:135]
	s_movk_i32 s2, 0x20ff
	s_nop 1
	v_add_u32_e32 v16, 0xb0, v179
	v_cmp_lt_i32_e32 vcc, s2, v16
	s_nop 1
	v_cndmask_b32_e32 v17, 0, v228, vcc
	v_add_u32_e32 v20, v17, v16
	v_cmp_lt_i32_e64 s[42:43], s81, v20
	s_and_saveexec_b64 s[2:3], s[42:43]
	s_xor_b64 s[2:3], exec, s[2:3]
	v_cndmask_b32_e32 v16, 0, v230, vcc
	s_movk_i32 s4, 0xff00
	v_add3_u32 v166, v20, v16, s4
	v_mov_b64_e32 v[16:17], v[166:167]
	s_or_saveexec_b64 s[4:5], s[2:3]
	v_mov_b64_e32 v[18:19], s[48:49]
	s_xor_b64 exec, exec, s[4:5]
	s_cbranch_execz .LBB0_833
	v_cndmask_b32_e32 v16, 0, v229, vcc
	v_add_u32_e32 v16, v20, v16
	v_ashrrev_i32_e32 v17, 31, v16
	v_mov_b64_e32 v[18:19], s[46:47]
	s_branch .LBB0_833
